# conv layers: z stored chunk-major too (gate_b epilogue stores, halo fix), out-projection A always chunk-major
# speedup vs baseline: 1.0184x; 1.0021x over previous
; __device__ __forceinline__ unsigned cvt_pk_bf16(float lo, float hi) { f32x2_t v = {lo, hi}; bf16x2_t b = __builtin_convertvector(v, bf16x2_t); return __builtin_bit_cast(unsigned, b); }
;     __device__ __forceinline__ void operator()(const f32x4 (&acc)[2][2][4][2], const Unit& u, int wr, int wc, int fr, int fq) const {
;     ...
;                     for (int m = 0; m < 4; ++m) { const int row = row0 + ai * HALF + m * 16, sq = row & 8191, lr = row & 255; const float r = rr[ai][m];
;                         const bool up_in = lr != 0, dn_in = lr != 255, up_halo = !up_in && sq != 0, dn_halo = !dn_in && sq != 8191;
;                         const bf16_t* up = U + (size_t)row * 1024 + col; const u32x4 z0 = {0u, 0u, 0u, 0u};
;                         const u32x4 uc = *(const u32x4*)up, ul = up_in ? *(const u32x4*)(up - 1024) : z0, ur = dn_in ? *(const u32x4*)(up + 1024) : z0;
;                         const f32x4 b0 = acc[ai][bj][m][0] * r, b1 = acc[ai][bj][m][1] * r;
;                         u32x4 w;
;                         w.x = cvt_pk_bf16(b0[0] * (k0a[0] * bf_lo(ul.x) + k1a[0] * bf_lo(uc.x) + k2a[0] * bf_lo(ur.x)), b0[1] * (k0a[1] * bf_hi(ul.x) + k1a[1] * bf_hi(uc.x) + k2a[1] * bf_hi(ur.x)));
;                         w.y = cvt_pk_bf16(b0[2] * (k0a[2] * bf_lo(ul.y) + k1a[2] * bf_lo(uc.y) + k2a[2] * bf_lo(ur.y)), b0[3] * (k0a[3] * bf_hi(ul.y) + k1a[3] * bf_hi(uc.y) + k2a[3] * bf_hi(ur.y)));
;                         w.z = cvt_pk_bf16(b1[0] * (k0b[0] * bf_lo(ul.z) + k1b[0] * bf_lo(uc.z) + k2b[0] * bf_lo(ur.z)), b1[1] * (k0b[1] * bf_hi(ul.z) + k1b[1] * bf_hi(uc.z) + k2b[1] * bf_hi(ur.z)));
;                         w.w = cvt_pk_bf16(b1[2] * (k0b[2] * bf_lo(ul.w) + k1b[2] * bf_lo(uc.w) + k2b[2] * bf_lo(ur.w)), b1[3] * (k0b[3] * bf_hi(ul.w) + k1b[3] * bf_hi(uc.w) + k2b[3] * bf_hi(ur.w)));
;                         if (up_halo || dn_halo) { const size_t ho = (size_t)(2 * u.pm + (dn_halo ? 1 : 0)) * 1024 + col;
;                             u32x4 bw; bw.x = cvt_pk_bf16(b0[0], b0[1]); bw.y = cvt_pk_bf16(b0[2], b0[3]); bw.z = cvt_pk_bf16(b1[0], b1[1]); bw.w = cvt_pk_bf16(b1[2], b1[3]);
;                             *(u32x4*)(HZ + ho) = w; *(u32x4*)(HBg + ho) = bw; }
;                         else *(u32x4*)(Z + (size_t)row * 1024 + col) = w; }
.LBB0_296:
	s_or_b64 exec, exec, s[14:15]
	s_waitcnt lgkmcnt(0)
	v_lshlrev_b32_e32 v216, 16, v162
	v_and_b32_e32 v217, 0xffff0000, v162
	v_lshlrev_b32_e32 v162, 16, v163
	v_and_b32_e32 v163, 0xffff0000, v163
	v_lshlrev_b32_e32 v218, 16, v158
	v_and_b32_e32 v219, 0xffff0000, v158
	v_pk_mul_f32 v[162:163], v[152:153], v[162:163]
	v_lshlrev_b32_e32 v158, 16, v159
	v_and_b32_e32 v159, 0xffff0000, v159
	v_pk_fma_f32 v[158:159], v[148:149], v[158:159], v[162:163]
	v_lshlrev_b32_e32 v162, 16, v155
	v_and_b32_e32 v163, 0xffff0000, v155
	v_pk_mul_f32 v[208:209], v[124:125], v[198:199] op_sel_hi:[1,0]
	v_pk_fma_f32 v[158:159], v[144:145], v[162:163], v[158:159]
	v_lshlrev_b32_e32 v162, 16, v160
	v_pk_mul_f32 v[158:159], v[208:209], v[158:159]
	v_and_b32_e32 v163, 0xffff0000, v160
	v_cvt_pk_bf16_f32 v155, v158, v159
	v_lshlrev_b32_e32 v158, 16, v164
	v_and_b32_e32 v159, 0xffff0000, v164
	v_pk_mul_f32 v[158:159], v[130:131], v[158:159]
	v_pk_mul_f32 v[214:215], v[118:119], v[198:199] op_sel_hi:[1,0]
	v_pk_fma_f32 v[158:159], v[134:135], v[162:163], v[158:159]
	v_lshlrev_b32_e32 v162, 16, v156
	v_and_b32_e32 v163, 0xffff0000, v156
	v_pk_fma_f32 v[158:159], v[138:139], v[162:163], v[158:159]
	v_and_b32_e32 v168, 0x1fff, v202
	v_pk_mul_f32 v[158:159], v[214:215], v[158:159]
	v_pk_mul_f32 v[216:217], v[150:151], v[216:217]
	v_cvt_pk_bf16_f32 v156, v158, v159
	v_lshlrev_b32_e32 v158, 16, v165
	v_and_b32_e32 v159, 0xffff0000, v165
	v_pk_mul_f32 v[158:159], v[132:133], v[158:159]
	v_lshlrev_b32_e32 v160, 16, v161
	v_and_b32_e32 v161, 0xffff0000, v161
	v_cmp_ne_u32_e32 vcc, 0, v168
	s_movk_i32 s14, 0x1fff
	v_pk_fma_f32 v[216:217], v[146:147], v[218:219], v[216:217]
	v_lshlrev_b32_e32 v218, 16, v154
	v_and_b32_e32 v219, 0xffff0000, v154
	v_pk_fma_f32 v[158:159], v[136:137], v[160:161], v[158:159]
	v_lshlrev_b32_e32 v160, 16, v157
	v_and_b32_e32 v161, 0xffff0000, v157
	s_and_b64 s[10:11], s[10:11], vcc
	v_cmp_ne_u32_e32 vcc, s14, v168
	v_pk_mul_f32 v[210:211], v[122:123], v[198:199] op_sel_hi:[1,0]
	v_pk_mul_f32 v[212:213], v[120:121], v[198:199] op_sel_hi:[1,0]
	v_pk_fma_f32 v[216:217], v[142:143], v[218:219], v[216:217]
	v_pk_fma_f32 v[158:159], v[140:141], v[160:161], v[158:159]
	v_lshlrev_b64 v[204:205], 10, v[202:203]
	s_and_b64 s[12:13], s[12:13], vcc
	v_pk_mul_f32 v[216:217], v[210:211], v[216:217]
	v_pk_mul_f32 v[158:159], v[212:213], v[158:159]
	v_cvt_pk_bf16_f32 v154, v216, v217
	v_cvt_pk_bf16_f32 v157, v158, v159
	s_nor_b64 s[10:11], s[10:11], s[12:13]
	v_lshl_add_u64 v[204:205], v[204:205], 1, s[74:75]
	s_and_saveexec_b64 s[14:15], s[10:11]
	s_xor_b64 s[14:15], exec, s[14:15]
	s_cbranch_execz .LBB0_298
	v_lshl_add_u64 v[158:159], v[206:207], 1, v[204:205]
	v_subrev_u32_e32 v172, s74, v158
	v_bfe_u32 v174, v172, 4, 7
	v_lshrrev_b32_e32 v172, 11, v172
	v_lshlrev_b32_e32 v174, 18, v174
	v_lshl_or_b32 v172, v172, 4, v174
	v_mov_b32_e32 v173, 0
	v_lshl_add_u64 v[172:173], s[74:75], 0, v[172:173]
	global_store_dwordx4 v[172:173], v[154:157], off

; __device__ __forceinline__ unsigned cvt_pk_bf16(float lo, float hi) { f32x2_t v = {lo, hi}; bf16x2_t b = __builtin_convertvector(v, bf16x2_t); return __builtin_bit_cast(unsigned, b); }
;     __device__ __forceinline__ void operator()(const f32x4 (&acc)[2][2][4][2], const Unit& u, int wr, int wc, int fr, int fq) const {
;     ...
;                     for (int m = 0; m < 4; ++m) { const int row = row0 + ai * HALF + m * 16, sq = row & 8191, lr = row & 255; const float r = rr[ai][m];
;                         const bool up_in = lr != 0, dn_in = lr != 255, up_halo = !up_in && sq != 0, dn_halo = !dn_in && sq != 8191;
;                         const bf16_t* up = U + (size_t)row * 1024 + col; const u32x4 z0 = {0u, 0u, 0u, 0u};
;                         const u32x4 uc = *(const u32x4*)up, ul = up_in ? *(const u32x4*)(up - 1024) : z0, ur = dn_in ? *(const u32x4*)(up + 1024) : z0;
;                         const f32x4 b0 = acc[ai][bj][m][0] * r, b1 = acc[ai][bj][m][1] * r;
;                         u32x4 w;
;                         w.x = cvt_pk_bf16(b0[0] * (k0a[0] * bf_lo(ul.x) + k1a[0] * bf_lo(uc.x) + k2a[0] * bf_lo(ur.x)), b0[1] * (k0a[1] * bf_hi(ul.x) + k1a[1] * bf_hi(uc.x) + k2a[1] * bf_hi(ur.x)));
;                         w.y = cvt_pk_bf16(b0[2] * (k0a[2] * bf_lo(ul.y) + k1a[2] * bf_lo(uc.y) + k2a[2] * bf_lo(ur.y)), b0[3] * (k0a[3] * bf_hi(ul.y) + k1a[3] * bf_hi(uc.y) + k2a[3] * bf_hi(ur.y)));
;                         w.z = cvt_pk_bf16(b1[0] * (k0b[0] * bf_lo(ul.z) + k1b[0] * bf_lo(uc.z) + k2b[0] * bf_lo(ur.z)), b1[1] * (k0b[1] * bf_hi(ul.z) + k1b[1] * bf_hi(uc.z) + k2b[1] * bf_hi(ur.z)));
;                         w.w = cvt_pk_bf16(b1[2] * (k0b[2] * bf_lo(ul.w) + k1b[2] * bf_lo(uc.w) + k2b[2] * bf_lo(ur.w)), b1[3] * (k0b[3] * bf_hi(ul.w) + k1b[3] * bf_hi(uc.w) + k2b[3] * bf_hi(ur.w)));
;                         if (up_halo || dn_halo) { const size_t ho = (size_t)(2 * u.pm + (dn_halo ? 1 : 0)) * 1024 + col;
;                             u32x4 bw; bw.x = cvt_pk_bf16(b0[0], b0[1]); bw.y = cvt_pk_bf16(b0[2], b0[3]); bw.z = cvt_pk_bf16(b1[0], b1[1]); bw.w = cvt_pk_bf16(b1[2], b1[3]);
;                             *(u32x4*)(HZ + ho) = w; *(u32x4*)(HBg + ho) = bw; }
;                         else *(u32x4*)(Z + (size_t)row * 1024 + col) = w; }
.LBB0_304:
	s_or_b64 exec, exec, s[20:21]
	v_lshlrev_b64 v[220:221], 10, v[208:209]
	v_and_b32_e32 v168, 0x1fff, v208
	s_waitcnt lgkmcnt(0)
	v_lshlrev_b32_e32 v208, 16, v162
	v_and_b32_e32 v209, 0xffff0000, v162
	v_lshlrev_b32_e32 v162, 16, v163
	v_and_b32_e32 v163, 0xffff0000, v163
	v_lshlrev_b32_e32 v222, 16, v158
	v_and_b32_e32 v223, 0xffff0000, v158
	v_pk_mul_f32 v[162:163], v[152:153], v[162:163]
	v_lshlrev_b32_e32 v158, 16, v159
	v_and_b32_e32 v159, 0xffff0000, v159
	v_pk_fma_f32 v[158:159], v[148:149], v[158:159], v[162:163]
	v_lshlrev_b32_e32 v162, 16, v155
	v_and_b32_e32 v163, 0xffff0000, v155
	v_pk_mul_f32 v[212:213], v[112:113], v[196:197] op_sel_hi:[1,0]
	v_pk_fma_f32 v[158:159], v[144:145], v[162:163], v[158:159]
	v_lshlrev_b32_e32 v162, 16, v160
	v_pk_mul_f32 v[158:159], v[212:213], v[158:159]
	v_and_b32_e32 v163, 0xffff0000, v160
	v_cvt_pk_bf16_f32 v155, v158, v159
	v_lshlrev_b32_e32 v158, 16, v164
	v_and_b32_e32 v159, 0xffff0000, v164
	v_pk_mul_f32 v[158:159], v[130:131], v[158:159]
	v_pk_mul_f32 v[218:219], v[102:103], v[196:197] op_sel_hi:[1,0]
	v_pk_fma_f32 v[158:159], v[134:135], v[162:163], v[158:159]
	v_lshlrev_b32_e32 v162, 16, v156
	v_and_b32_e32 v163, 0xffff0000, v156
	v_pk_fma_f32 v[158:159], v[138:139], v[162:163], v[158:159]
	v_pk_mul_f32 v[208:209], v[150:151], v[208:209]
	v_pk_mul_f32 v[158:159], v[218:219], v[158:159]
	v_lshlrev_b32_e32 v160, 16, v161
	v_cvt_pk_bf16_f32 v156, v158, v159
	v_lshlrev_b32_e32 v158, 16, v165
	v_and_b32_e32 v159, 0xffff0000, v165
	v_pk_mul_f32 v[158:159], v[132:133], v[158:159]
	v_and_b32_e32 v161, 0xffff0000, v161
	v_cmp_ne_u32_e32 vcc, 0, v168
	s_movk_i32 s20, 0x1fff
	v_pk_fma_f32 v[208:209], v[146:147], v[222:223], v[208:209]
	v_lshlrev_b32_e32 v222, 16, v154
	v_and_b32_e32 v223, 0xffff0000, v154
	v_pk_fma_f32 v[158:159], v[136:137], v[160:161], v[158:159]
	v_lshlrev_b32_e32 v160, 16, v157
	v_and_b32_e32 v161, 0xffff0000, v157
	s_and_b64 s[16:17], s[16:17], vcc
	v_cmp_ne_u32_e32 vcc, s20, v168
	v_pk_mul_f32 v[214:215], v[110:111], v[196:197] op_sel_hi:[1,0]
	v_pk_mul_f32 v[216:217], v[104:105], v[196:197] op_sel_hi:[1,0]
	v_pk_fma_f32 v[208:209], v[142:143], v[222:223], v[208:209]
	v_pk_fma_f32 v[158:159], v[140:141], v[160:161], v[158:159]
	s_and_b64 s[18:19], s[18:19], vcc
	v_pk_mul_f32 v[208:209], v[214:215], v[208:209]
	v_pk_mul_f32 v[158:159], v[216:217], v[158:159]
	v_cvt_pk_bf16_f32 v154, v208, v209
	v_cvt_pk_bf16_f32 v157, v158, v159
	s_nor_b64 s[16:17], s[16:17], s[18:19]
	v_lshl_add_u64 v[208:209], v[220:221], 1, s[74:75]
	s_and_saveexec_b64 s[20:21], s[16:17]
	s_xor_b64 s[20:21], exec, s[20:21]
	s_cbranch_execz .LBB0_306
	v_lshl_add_u64 v[158:159], v[206:207], 1, v[208:209]
	v_subrev_u32_e32 v172, s74, v158
	v_bfe_u32 v174, v172, 4, 7
	v_lshrrev_b32_e32 v172, 11, v172
	v_lshlrev_b32_e32 v174, 18, v174
	v_lshl_or_b32 v172, v172, 4, v174
	v_mov_b32_e32 v173, 0
	v_lshl_add_u64 v[172:173], s[74:75], 0, v[172:173]
	global_store_dwordx4 v[172:173], v[154:157], off

; __device__ __forceinline__ unsigned cvt_pk_bf16(float lo, float hi) { f32x2_t v = {lo, hi}; bf16x2_t b = __builtin_convertvector(v, bf16x2_t); return __builtin_bit_cast(unsigned, b); }
;     __device__ __forceinline__ void operator()(const f32x4 (&acc)[2][2][4][2], const Unit& u, int wr, int wc, int fr, int fq) const {
;     ...
;                     for (int m = 0; m < 4; ++m) { const int row = row0 + ai * HALF + m * 16, sq = row & 8191, lr = row & 255; const float r = rr[ai][m];
;                         const bool up_in = lr != 0, dn_in = lr != 255, up_halo = !up_in && sq != 0, dn_halo = !dn_in && sq != 8191;
;                         const bf16_t* up = U + (size_t)row * 1024 + col; const u32x4 z0 = {0u, 0u, 0u, 0u};
;                         const u32x4 uc = *(const u32x4*)up, ul = up_in ? *(const u32x4*)(up - 1024) : z0, ur = dn_in ? *(const u32x4*)(up + 1024) : z0;
;                         const f32x4 b0 = acc[ai][bj][m][0] * r, b1 = acc[ai][bj][m][1] * r;
;                         u32x4 w;
;                         w.x = cvt_pk_bf16(b0[0] * (k0a[0] * bf_lo(ul.x) + k1a[0] * bf_lo(uc.x) + k2a[0] * bf_lo(ur.x)), b0[1] * (k0a[1] * bf_hi(ul.x) + k1a[1] * bf_hi(uc.x) + k2a[1] * bf_hi(ur.x)));
;                         w.y = cvt_pk_bf16(b0[2] * (k0a[2] * bf_lo(ul.y) + k1a[2] * bf_lo(uc.y) + k2a[2] * bf_lo(ur.y)), b0[3] * (k0a[3] * bf_hi(ul.y) + k1a[3] * bf_hi(uc.y) + k2a[3] * bf_hi(ur.y)));
;                         w.z = cvt_pk_bf16(b1[0] * (k0b[0] * bf_lo(ul.z) + k1b[0] * bf_lo(uc.z) + k2b[0] * bf_lo(ur.z)), b1[1] * (k0b[1] * bf_hi(ul.z) + k1b[1] * bf_hi(uc.z) + k2b[1] * bf_hi(ur.z)));
;                         w.w = cvt_pk_bf16(b1[2] * (k0b[2] * bf_lo(ul.w) + k1b[2] * bf_lo(uc.w) + k2b[2] * bf_lo(ur.w)), b1[3] * (k0b[3] * bf_hi(ul.w) + k1b[3] * bf_hi(uc.w) + k2b[3] * bf_hi(ur.w)));
;                         if (up_halo || dn_halo) { const size_t ho = (size_t)(2 * u.pm + (dn_halo ? 1 : 0)) * 1024 + col;
;                             u32x4 bw; bw.x = cvt_pk_bf16(b0[0], b0[1]); bw.y = cvt_pk_bf16(b0[2], b0[3]); bw.z = cvt_pk_bf16(b1[0], b1[1]); bw.w = cvt_pk_bf16(b1[2], b1[3]);
;                             *(u32x4*)(HZ + ho) = w; *(u32x4*)(HBg + ho) = bw; }
;                         else *(u32x4*)(Z + (size_t)row * 1024 + col) = w; }
.LBB0_312:
	s_or_b64 exec, exec, s[34:35]
	v_lshlrev_b64 v[224:225], 10, v[212:213]
	v_and_b32_e32 v168, 0x1fff, v212
	s_waitcnt lgkmcnt(0)
	v_lshlrev_b32_e32 v212, 16, v162
	v_and_b32_e32 v213, 0xffff0000, v162
	v_lshlrev_b32_e32 v162, 16, v163
	v_and_b32_e32 v163, 0xffff0000, v163
	v_lshlrev_b32_e32 v226, 16, v158
	v_and_b32_e32 v227, 0xffff0000, v158
	v_pk_mul_f32 v[162:163], v[152:153], v[162:163]
	v_lshlrev_b32_e32 v158, 16, v159
	v_and_b32_e32 v159, 0xffff0000, v159
	v_pk_fma_f32 v[158:159], v[148:149], v[158:159], v[162:163]
	v_lshlrev_b32_e32 v162, 16, v155
	v_and_b32_e32 v163, 0xffff0000, v155
	v_pk_mul_f32 v[216:217], v[96:97], v[192:193] op_sel_hi:[1,0]
	v_pk_fma_f32 v[158:159], v[144:145], v[162:163], v[158:159]
	v_lshlrev_b32_e32 v162, 16, v160
	v_pk_mul_f32 v[158:159], v[216:217], v[158:159]
	v_and_b32_e32 v163, 0xffff0000, v160
	v_cvt_pk_bf16_f32 v155, v158, v159
	v_lshlrev_b32_e32 v158, 16, v164
	v_and_b32_e32 v159, 0xffff0000, v164
	v_pk_mul_f32 v[158:159], v[130:131], v[158:159]
	v_pk_mul_f32 v[222:223], v[86:87], v[192:193] op_sel_hi:[1,0]
	v_pk_fma_f32 v[158:159], v[134:135], v[162:163], v[158:159]
	v_lshlrev_b32_e32 v162, 16, v156
	v_and_b32_e32 v163, 0xffff0000, v156
	v_pk_fma_f32 v[158:159], v[138:139], v[162:163], v[158:159]
	v_pk_mul_f32 v[212:213], v[150:151], v[212:213]
	v_pk_mul_f32 v[158:159], v[222:223], v[158:159]
	v_lshlrev_b32_e32 v160, 16, v161
	v_cvt_pk_bf16_f32 v156, v158, v159
	v_lshlrev_b32_e32 v158, 16, v165
	v_and_b32_e32 v159, 0xffff0000, v165
	v_pk_mul_f32 v[158:159], v[132:133], v[158:159]
	v_and_b32_e32 v161, 0xffff0000, v161
	v_cmp_ne_u32_e32 vcc, 0, v168
	s_movk_i32 s34, 0x1fff
	v_pk_fma_f32 v[212:213], v[146:147], v[226:227], v[212:213]
	v_lshlrev_b32_e32 v226, 16, v154
	v_and_b32_e32 v227, 0xffff0000, v154
	v_pk_fma_f32 v[158:159], v[136:137], v[160:161], v[158:159]
	v_lshlrev_b32_e32 v160, 16, v157
	v_and_b32_e32 v161, 0xffff0000, v157
	s_and_b64 s[22:23], s[22:23], vcc
	v_cmp_ne_u32_e32 vcc, s34, v168
	v_pk_mul_f32 v[218:219], v[94:95], v[192:193] op_sel_hi:[1,0]
	v_pk_mul_f32 v[220:221], v[88:89], v[192:193] op_sel_hi:[1,0]
	v_pk_fma_f32 v[212:213], v[142:143], v[226:227], v[212:213]
	v_pk_fma_f32 v[158:159], v[140:141], v[160:161], v[158:159]
	s_and_b64 s[24:25], s[24:25], vcc
	v_pk_mul_f32 v[212:213], v[218:219], v[212:213]
	v_pk_mul_f32 v[158:159], v[220:221], v[158:159]
	v_cvt_pk_bf16_f32 v154, v212, v213
	v_cvt_pk_bf16_f32 v157, v158, v159
	s_nor_b64 s[22:23], s[22:23], s[24:25]
	v_lshl_add_u64 v[212:213], v[224:225], 1, s[74:75]
	s_and_saveexec_b64 s[34:35], s[22:23]
	s_xor_b64 s[34:35], exec, s[34:35]
	s_cbranch_execz .LBB0_314
	v_lshl_add_u64 v[158:159], v[206:207], 1, v[212:213]
	v_subrev_u32_e32 v172, s74, v158
	v_bfe_u32 v174, v172, 4, 7
	v_lshrrev_b32_e32 v172, 11, v172
	v_lshlrev_b32_e32 v174, 18, v174
	v_lshl_or_b32 v172, v172, 4, v174
	v_mov_b32_e32 v173, 0
	v_lshl_add_u64 v[172:173], s[74:75], 0, v[172:173]
	global_store_dwordx4 v[172:173], v[154:157], off

; __device__ __forceinline__ unsigned cvt_pk_bf16(float lo, float hi) { f32x2_t v = {lo, hi}; bf16x2_t b = __builtin_convertvector(v, bf16x2_t); return __builtin_bit_cast(unsigned, b); }
;     __device__ __forceinline__ void operator()(const f32x4 (&acc)[2][2][4][2], const Unit& u, int wr, int wc, int fr, int fq) const {
;     ...
;                     for (int m = 0; m < 4; ++m) { const int row = row0 + ai * HALF + m * 16, sq = row & 8191, lr = row & 255; const float r = rr[ai][m];
;                         const bool up_in = lr != 0, dn_in = lr != 255, up_halo = !up_in && sq != 0, dn_halo = !dn_in && sq != 8191;
;                         const bf16_t* up = U + (size_t)row * 1024 + col; const u32x4 z0 = {0u, 0u, 0u, 0u};
;                         const u32x4 uc = *(const u32x4*)up, ul = up_in ? *(const u32x4*)(up - 1024) : z0, ur = dn_in ? *(const u32x4*)(up + 1024) : z0;
;                         const f32x4 b0 = acc[ai][bj][m][0] * r, b1 = acc[ai][bj][m][1] * r;
;                         u32x4 w;
;                         w.x = cvt_pk_bf16(b0[0] * (k0a[0] * bf_lo(ul.x) + k1a[0] * bf_lo(uc.x) + k2a[0] * bf_lo(ur.x)), b0[1] * (k0a[1] * bf_hi(ul.x) + k1a[1] * bf_hi(uc.x) + k2a[1] * bf_hi(ur.x)));
;                         w.y = cvt_pk_bf16(b0[2] * (k0a[2] * bf_lo(ul.y) + k1a[2] * bf_lo(uc.y) + k2a[2] * bf_lo(ur.y)), b0[3] * (k0a[3] * bf_hi(ul.y) + k1a[3] * bf_hi(uc.y) + k2a[3] * bf_hi(ur.y)));
;                         w.z = cvt_pk_bf16(b1[0] * (k0b[0] * bf_lo(ul.z) + k1b[0] * bf_lo(uc.z) + k2b[0] * bf_lo(ur.z)), b1[1] * (k0b[1] * bf_hi(ul.z) + k1b[1] * bf_hi(uc.z) + k2b[1] * bf_hi(ur.z)));
;                         w.w = cvt_pk_bf16(b1[2] * (k0b[2] * bf_lo(ul.w) + k1b[2] * bf_lo(uc.w) + k2b[2] * bf_lo(ur.w)), b1[3] * (k0b[3] * bf_hi(ul.w) + k1b[3] * bf_hi(uc.w) + k2b[3] * bf_hi(ur.w)));
;                         if (up_halo || dn_halo) { const size_t ho = (size_t)(2 * u.pm + (dn_halo ? 1 : 0)) * 1024 + col;
;                             u32x4 bw; bw.x = cvt_pk_bf16(b0[0], b0[1]); bw.y = cvt_pk_bf16(b0[2], b0[3]); bw.z = cvt_pk_bf16(b1[0], b1[1]); bw.w = cvt_pk_bf16(b1[2], b1[3]);
;                             *(u32x4*)(HZ + ho) = w; *(u32x4*)(HBg + ho) = bw; }
;                         else *(u32x4*)(Z + (size_t)row * 1024 + col) = w; }
.LBB0_320:
	s_or_b64 exec, exec, s[44:45]
	v_lshlrev_b64 v[228:229], 10, v[216:217]
	v_and_b32_e32 v168, 0x1fff, v216
	s_waitcnt lgkmcnt(0)
	v_lshlrev_b32_e32 v216, 16, v162
	v_and_b32_e32 v217, 0xffff0000, v162
	v_lshlrev_b32_e32 v162, 16, v163
	v_and_b32_e32 v163, 0xffff0000, v163
	v_lshlrev_b32_e32 v230, 16, v158
	v_and_b32_e32 v231, 0xffff0000, v158
	v_pk_mul_f32 v[162:163], v[152:153], v[162:163]
	v_lshlrev_b32_e32 v158, 16, v159
	v_and_b32_e32 v159, 0xffff0000, v159
	v_pk_fma_f32 v[158:159], v[148:149], v[158:159], v[162:163]
	v_lshlrev_b32_e32 v162, 16, v155
	v_and_b32_e32 v163, 0xffff0000, v155
	v_pk_mul_f32 v[220:221], v[80:81], v[194:195] op_sel_hi:[1,0]
	v_pk_fma_f32 v[158:159], v[144:145], v[162:163], v[158:159]
	v_lshlrev_b32_e32 v162, 16, v160
	v_pk_mul_f32 v[158:159], v[220:221], v[158:159]
	v_and_b32_e32 v163, 0xffff0000, v160
	v_cvt_pk_bf16_f32 v155, v158, v159
	v_lshlrev_b32_e32 v158, 16, v164
	v_and_b32_e32 v159, 0xffff0000, v164
	v_pk_mul_f32 v[158:159], v[130:131], v[158:159]
	v_pk_mul_f32 v[226:227], v[70:71], v[194:195] op_sel_hi:[1,0]
	v_pk_fma_f32 v[158:159], v[134:135], v[162:163], v[158:159]
	v_lshlrev_b32_e32 v162, 16, v156
	v_and_b32_e32 v163, 0xffff0000, v156
	v_pk_fma_f32 v[158:159], v[138:139], v[162:163], v[158:159]
	v_pk_mul_f32 v[216:217], v[150:151], v[216:217]
	v_pk_mul_f32 v[158:159], v[226:227], v[158:159]
	v_lshlrev_b32_e32 v160, 16, v161
	v_cvt_pk_bf16_f32 v156, v158, v159
	v_lshlrev_b32_e32 v158, 16, v165
	v_and_b32_e32 v159, 0xffff0000, v165
	v_pk_mul_f32 v[158:159], v[132:133], v[158:159]
	v_and_b32_e32 v161, 0xffff0000, v161
	v_cmp_ne_u32_e32 vcc, 0, v168
	s_movk_i32 s38, 0x1fff
	v_pk_fma_f32 v[216:217], v[146:147], v[230:231], v[216:217]
	v_lshlrev_b32_e32 v230, 16, v154
	v_and_b32_e32 v231, 0xffff0000, v154
	v_pk_fma_f32 v[158:159], v[136:137], v[160:161], v[158:159]
	v_lshlrev_b32_e32 v160, 16, v157
	v_and_b32_e32 v161, 0xffff0000, v157
	s_and_b64 s[34:35], s[34:35], vcc
	v_cmp_ne_u32_e32 vcc, s38, v168
	v_pk_mul_f32 v[222:223], v[78:79], v[194:195] op_sel_hi:[1,0]
	v_pk_mul_f32 v[224:225], v[72:73], v[194:195] op_sel_hi:[1,0]
	v_pk_fma_f32 v[216:217], v[142:143], v[230:231], v[216:217]
	v_pk_fma_f32 v[158:159], v[140:141], v[160:161], v[158:159]
	s_and_b64 s[42:43], s[42:43], vcc
	v_pk_mul_f32 v[216:217], v[222:223], v[216:217]
	v_pk_mul_f32 v[158:159], v[224:225], v[158:159]
	v_cvt_pk_bf16_f32 v154, v216, v217
	v_cvt_pk_bf16_f32 v157, v158, v159
	s_nor_b64 s[34:35], s[34:35], s[42:43]
	v_lshl_add_u64 v[216:217], v[228:229], 1, s[74:75]
	s_and_saveexec_b64 s[44:45], s[34:35]
	s_xor_b64 s[44:45], exec, s[44:45]
	s_cbranch_execz .LBB0_322
	v_lshl_add_u64 v[158:159], v[206:207], 1, v[216:217]
	v_subrev_u32_e32 v172, s74, v158
	v_bfe_u32 v174, v172, 4, 7
	v_lshrrev_b32_e32 v172, 11, v172
	v_lshlrev_b32_e32 v174, 18, v174
	v_lshl_or_b32 v172, v172, 4, v174
	v_mov_b32_e32 v173, 0
	v_lshl_add_u64 v[172:173], s[74:75], 0, v[172:173]
	global_store_dwordx4 v[172:173], v[154:157], off

; __device__ __forceinline__ unsigned cvt_pk_bf16(float lo, float hi) { f32x2_t v = {lo, hi}; bf16x2_t b = __builtin_convertvector(v, bf16x2_t); return __builtin_bit_cast(unsigned, b); }
;     __device__ __forceinline__ void operator()(const f32x4 (&acc)[2][2][4][2], const Unit& u, int wr, int wc, int fr, int fq) const {
;     ...
;                     for (int m = 0; m < 4; ++m) { const int row = row0 + ai * HALF + m * 16, sq = row & 8191, lr = row & 255; const float r = rr[ai][m];
;                         const bool up_in = lr != 0, dn_in = lr != 255, up_halo = !up_in && sq != 0, dn_halo = !dn_in && sq != 8191;
;                         const bf16_t* up = U + (size_t)row * 1024 + col; const u32x4 z0 = {0u, 0u, 0u, 0u};
;                         const u32x4 uc = *(const u32x4*)up, ul = up_in ? *(const u32x4*)(up - 1024) : z0, ur = dn_in ? *(const u32x4*)(up + 1024) : z0;
;                         const f32x4 b0 = acc[ai][bj][m][0] * r, b1 = acc[ai][bj][m][1] * r;
;                         u32x4 w;
;                         w.x = cvt_pk_bf16(b0[0] * (k0a[0] * bf_lo(ul.x) + k1a[0] * bf_lo(uc.x) + k2a[0] * bf_lo(ur.x)), b0[1] * (k0a[1] * bf_hi(ul.x) + k1a[1] * bf_hi(uc.x) + k2a[1] * bf_hi(ur.x)));
;                         w.y = cvt_pk_bf16(b0[2] * (k0a[2] * bf_lo(ul.y) + k1a[2] * bf_lo(uc.y) + k2a[2] * bf_lo(ur.y)), b0[3] * (k0a[3] * bf_hi(ul.y) + k1a[3] * bf_hi(uc.y) + k2a[3] * bf_hi(ur.y)));
;                         w.z = cvt_pk_bf16(b1[0] * (k0b[0] * bf_lo(ul.z) + k1b[0] * bf_lo(uc.z) + k2b[0] * bf_lo(ur.z)), b1[1] * (k0b[1] * bf_hi(ul.z) + k1b[1] * bf_hi(uc.z) + k2b[1] * bf_hi(ur.z)));
;                         w.w = cvt_pk_bf16(b1[2] * (k0b[2] * bf_lo(ul.w) + k1b[2] * bf_lo(uc.w) + k2b[2] * bf_lo(ur.w)), b1[3] * (k0b[3] * bf_hi(ul.w) + k1b[3] * bf_hi(uc.w) + k2b[3] * bf_hi(ur.w)));
;                         if (up_halo || dn_halo) { const size_t ho = (size_t)(2 * u.pm + (dn_halo ? 1 : 0)) * 1024 + col;
;                             u32x4 bw; bw.x = cvt_pk_bf16(b0[0], b0[1]); bw.y = cvt_pk_bf16(b0[2], b0[3]); bw.z = cvt_pk_bf16(b1[0], b1[1]); bw.w = cvt_pk_bf16(b1[2], b1[3]);
;                             *(u32x4*)(HZ + ho) = w; *(u32x4*)(HBg + ho) = bw; }
;                         else *(u32x4*)(Z + (size_t)row * 1024 + col) = w; }
.LBB0_328:
	s_or_b64 exec, exec, s[56:57]
	v_lshlrev_b64 v[232:233], 10, v[220:221]
	v_and_b32_e32 v168, 0x1fff, v220
	s_waitcnt lgkmcnt(0)
	v_lshlrev_b32_e32 v220, 16, v162
	v_and_b32_e32 v221, 0xffff0000, v162
	v_lshlrev_b32_e32 v162, 16, v163
	v_and_b32_e32 v163, 0xffff0000, v163
	v_lshlrev_b32_e32 v234, 16, v158
	v_and_b32_e32 v235, 0xffff0000, v158
	v_pk_mul_f32 v[162:163], v[152:153], v[162:163]
	v_lshlrev_b32_e32 v158, 16, v159
	v_and_b32_e32 v159, 0xffff0000, v159
	v_pk_fma_f32 v[158:159], v[148:149], v[158:159], v[162:163]
	v_lshlrev_b32_e32 v162, 16, v155
	v_and_b32_e32 v163, 0xffff0000, v155
	v_pk_mul_f32 v[224:225], v[64:65], v[190:191] op_sel_hi:[1,0]
	v_pk_fma_f32 v[158:159], v[144:145], v[162:163], v[158:159]
	v_lshlrev_b32_e32 v162, 16, v160
	v_pk_mul_f32 v[158:159], v[224:225], v[158:159]
	v_and_b32_e32 v163, 0xffff0000, v160
	v_cvt_pk_bf16_f32 v155, v158, v159
	v_lshlrev_b32_e32 v158, 16, v164
	v_and_b32_e32 v159, 0xffff0000, v164
	v_pk_mul_f32 v[158:159], v[130:131], v[158:159]
	v_pk_mul_f32 v[230:231], v[54:55], v[190:191] op_sel_hi:[1,0]
	v_pk_fma_f32 v[158:159], v[134:135], v[162:163], v[158:159]
	v_lshlrev_b32_e32 v162, 16, v156
	v_and_b32_e32 v163, 0xffff0000, v156
	v_pk_fma_f32 v[158:159], v[138:139], v[162:163], v[158:159]
	v_pk_mul_f32 v[220:221], v[150:151], v[220:221]
	v_pk_mul_f32 v[158:159], v[230:231], v[158:159]
	v_lshlrev_b32_e32 v160, 16, v161
	v_cvt_pk_bf16_f32 v156, v158, v159
	v_lshlrev_b32_e32 v158, 16, v165
	v_and_b32_e32 v159, 0xffff0000, v165
	v_pk_mul_f32 v[158:159], v[132:133], v[158:159]
	v_and_b32_e32 v161, 0xffff0000, v161
	v_cmp_ne_u32_e32 vcc, 0, v168
	s_movk_i32 s38, 0x1fff
	v_pk_fma_f32 v[220:221], v[146:147], v[234:235], v[220:221]
	v_lshlrev_b32_e32 v234, 16, v154
	v_and_b32_e32 v235, 0xffff0000, v154
	v_pk_fma_f32 v[158:159], v[136:137], v[160:161], v[158:159]
	v_lshlrev_b32_e32 v160, 16, v157
	v_and_b32_e32 v161, 0xffff0000, v157
	s_and_b64 s[56:57], s[42:43], vcc
	v_cmp_ne_u32_e32 vcc, s38, v168
	v_pk_mul_f32 v[226:227], v[62:63], v[190:191] op_sel_hi:[1,0]
	v_pk_mul_f32 v[228:229], v[56:57], v[190:191] op_sel_hi:[1,0]
	v_pk_fma_f32 v[220:221], v[142:143], v[234:235], v[220:221]
	v_pk_fma_f32 v[158:159], v[140:141], v[160:161], v[158:159]
	s_and_b64 s[42:43], s[44:45], vcc
	v_pk_mul_f32 v[220:221], v[226:227], v[220:221]
	v_pk_mul_f32 v[158:159], v[228:229], v[158:159]
	v_cvt_pk_bf16_f32 v154, v220, v221
	v_cvt_pk_bf16_f32 v157, v158, v159
	s_nor_b64 s[44:45], s[56:57], s[42:43]
	v_lshl_add_u64 v[220:221], v[232:233], 1, s[74:75]
	s_and_saveexec_b64 s[56:57], s[44:45]
	s_xor_b64 s[56:57], exec, s[56:57]
	s_cbranch_execz .LBB0_330
	v_lshl_add_u64 v[158:159], v[206:207], 1, v[220:221]
	v_subrev_u32_e32 v172, s74, v158
	v_bfe_u32 v174, v172, 4, 7
	v_lshrrev_b32_e32 v172, 11, v172
	v_lshlrev_b32_e32 v174, 18, v174
	v_lshl_or_b32 v172, v172, 4, v174
	v_mov_b32_e32 v173, 0
	v_lshl_add_u64 v[172:173], s[74:75], 0, v[172:173]
	global_store_dwordx4 v[172:173], v[154:157], off

; __device__ __forceinline__ unsigned cvt_pk_bf16(float lo, float hi) { f32x2_t v = {lo, hi}; bf16x2_t b = __builtin_convertvector(v, bf16x2_t); return __builtin_bit_cast(unsigned, b); }
;     __device__ __forceinline__ void operator()(const f32x4 (&acc)[2][2][4][2], const Unit& u, int wr, int wc, int fr, int fq) const {
;     ...
;                     for (int m = 0; m < 4; ++m) { const int row = row0 + ai * HALF + m * 16, sq = row & 8191, lr = row & 255; const float r = rr[ai][m];
;                         const bool up_in = lr != 0, dn_in = lr != 255, up_halo = !up_in && sq != 0, dn_halo = !dn_in && sq != 8191;
;                         const bf16_t* up = U + (size_t)row * 1024 + col; const u32x4 z0 = {0u, 0u, 0u, 0u};
;                         const u32x4 uc = *(const u32x4*)up, ul = up_in ? *(const u32x4*)(up - 1024) : z0, ur = dn_in ? *(const u32x4*)(up + 1024) : z0;
;                         const f32x4 b0 = acc[ai][bj][m][0] * r, b1 = acc[ai][bj][m][1] * r;
;                         u32x4 w;
;                         w.x = cvt_pk_bf16(b0[0] * (k0a[0] * bf_lo(ul.x) + k1a[0] * bf_lo(uc.x) + k2a[0] * bf_lo(ur.x)), b0[1] * (k0a[1] * bf_hi(ul.x) + k1a[1] * bf_hi(uc.x) + k2a[1] * bf_hi(ur.x)));
;                         w.y = cvt_pk_bf16(b0[2] * (k0a[2] * bf_lo(ul.y) + k1a[2] * bf_lo(uc.y) + k2a[2] * bf_lo(ur.y)), b0[3] * (k0a[3] * bf_hi(ul.y) + k1a[3] * bf_hi(uc.y) + k2a[3] * bf_hi(ur.y)));
;                         w.z = cvt_pk_bf16(b1[0] * (k0b[0] * bf_lo(ul.z) + k1b[0] * bf_lo(uc.z) + k2b[0] * bf_lo(ur.z)), b1[1] * (k0b[1] * bf_hi(ul.z) + k1b[1] * bf_hi(uc.z) + k2b[1] * bf_hi(ur.z)));
;                         w.w = cvt_pk_bf16(b1[2] * (k0b[2] * bf_lo(ul.w) + k1b[2] * bf_lo(uc.w) + k2b[2] * bf_lo(ur.w)), b1[3] * (k0b[3] * bf_hi(ul.w) + k1b[3] * bf_hi(uc.w) + k2b[3] * bf_hi(ur.w)));
;                         if (up_halo || dn_halo) { const size_t ho = (size_t)(2 * u.pm + (dn_halo ? 1 : 0)) * 1024 + col;
;                             u32x4 bw; bw.x = cvt_pk_bf16(b0[0], b0[1]); bw.y = cvt_pk_bf16(b0[2], b0[3]); bw.z = cvt_pk_bf16(b1[0], b1[1]); bw.w = cvt_pk_bf16(b1[2], b1[3]);
;                             *(u32x4*)(HZ + ho) = w; *(u32x4*)(HBg + ho) = bw; }
;                         else *(u32x4*)(Z + (size_t)row * 1024 + col) = w; }
.LBB0_336:
	s_or_b64 exec, exec, s[78:79]
	v_lshlrev_b64 v[236:237], 10, v[224:225]
	v_and_b32_e32 v168, 0x1fff, v224
	s_waitcnt lgkmcnt(0)
	v_lshlrev_b32_e32 v224, 16, v162
	v_and_b32_e32 v225, 0xffff0000, v162
	v_lshlrev_b32_e32 v162, 16, v163
	v_and_b32_e32 v163, 0xffff0000, v163
	v_lshlrev_b32_e32 v238, 16, v158
	v_and_b32_e32 v239, 0xffff0000, v158
	v_pk_mul_f32 v[162:163], v[152:153], v[162:163]
	v_lshlrev_b32_e32 v158, 16, v159
	v_and_b32_e32 v159, 0xffff0000, v159
	v_pk_fma_f32 v[158:159], v[148:149], v[158:159], v[162:163]
	v_lshlrev_b32_e32 v162, 16, v155
	v_and_b32_e32 v163, 0xffff0000, v155
	v_pk_mul_f32 v[228:229], v[48:49], v[188:189] op_sel_hi:[1,0]
	v_pk_fma_f32 v[158:159], v[144:145], v[162:163], v[158:159]
	v_lshlrev_b32_e32 v162, 16, v160
	v_pk_mul_f32 v[158:159], v[228:229], v[158:159]
	v_and_b32_e32 v163, 0xffff0000, v160
	v_cvt_pk_bf16_f32 v155, v158, v159
	v_lshlrev_b32_e32 v158, 16, v164
	v_and_b32_e32 v159, 0xffff0000, v164
	v_pk_mul_f32 v[158:159], v[130:131], v[158:159]
	v_pk_mul_f32 v[234:235], v[38:39], v[188:189] op_sel_hi:[1,0]
	v_pk_fma_f32 v[158:159], v[134:135], v[162:163], v[158:159]
	v_lshlrev_b32_e32 v162, 16, v156
	v_and_b32_e32 v163, 0xffff0000, v156
	v_pk_fma_f32 v[158:159], v[138:139], v[162:163], v[158:159]
	v_pk_mul_f32 v[224:225], v[150:151], v[224:225]
	v_pk_mul_f32 v[158:159], v[234:235], v[158:159]
	v_lshlrev_b32_e32 v160, 16, v161
	v_cvt_pk_bf16_f32 v156, v158, v159
	v_lshlrev_b32_e32 v158, 16, v165
	v_and_b32_e32 v159, 0xffff0000, v165
	v_pk_mul_f32 v[158:159], v[132:133], v[158:159]
	v_and_b32_e32 v161, 0xffff0000, v161
	v_cmp_ne_u32_e32 vcc, 0, v168
	s_movk_i32 s38, 0x1fff
	v_pk_fma_f32 v[224:225], v[146:147], v[238:239], v[224:225]
	v_lshlrev_b32_e32 v238, 16, v154
	v_and_b32_e32 v239, 0xffff0000, v154
	v_pk_fma_f32 v[158:159], v[136:137], v[160:161], v[158:159]
	v_lshlrev_b32_e32 v160, 16, v157
	v_and_b32_e32 v161, 0xffff0000, v157
	s_and_b64 s[78:79], s[56:57], vcc
	v_cmp_ne_u32_e32 vcc, s38, v168
	v_pk_mul_f32 v[230:231], v[46:47], v[188:189] op_sel_hi:[1,0]
	v_pk_mul_f32 v[232:233], v[40:41], v[188:189] op_sel_hi:[1,0]
	v_pk_fma_f32 v[224:225], v[142:143], v[238:239], v[224:225]
	v_pk_fma_f32 v[158:159], v[140:141], v[160:161], v[158:159]
	s_and_b64 s[56:57], s[60:61], vcc
	v_pk_mul_f32 v[224:225], v[230:231], v[224:225]
	v_pk_mul_f32 v[158:159], v[232:233], v[158:159]
	v_cvt_pk_bf16_f32 v154, v224, v225
	v_cvt_pk_bf16_f32 v157, v158, v159
	s_nor_b64 s[92:93], s[78:79], s[56:57]
	v_lshl_add_u64 v[224:225], v[236:237], 1, s[74:75]
	s_and_saveexec_b64 s[60:61], s[92:93]
	s_xor_b64 s[60:61], exec, s[60:61]
	s_cbranch_execz .LBB0_338
	v_lshl_add_u64 v[158:159], v[206:207], 1, v[224:225]
	v_subrev_u32_e32 v172, s74, v158
	v_bfe_u32 v174, v172, 4, 7
	v_lshrrev_b32_e32 v172, 11, v172
	v_lshlrev_b32_e32 v174, 18, v174
	v_lshl_or_b32 v172, v172, 4, v174
	v_mov_b32_e32 v173, 0
	v_lshl_add_u64 v[172:173], s[74:75], 0, v[172:173]
	global_store_dwordx4 v[172:173], v[154:157], off

; __device__ __forceinline__ unsigned cvt_pk_bf16(float lo, float hi) { f32x2_t v = {lo, hi}; bf16x2_t b = __builtin_convertvector(v, bf16x2_t); return __builtin_bit_cast(unsigned, b); }
;     __device__ __forceinline__ void operator()(const f32x4 (&acc)[2][2][4][2], const Unit& u, int wr, int wc, int fr, int fq) const {
;     ...
;                     for (int m = 0; m < 4; ++m) { const int row = row0 + ai * HALF + m * 16, sq = row & 8191, lr = row & 255; const float r = rr[ai][m];
;                         const bool up_in = lr != 0, dn_in = lr != 255, up_halo = !up_in && sq != 0, dn_halo = !dn_in && sq != 8191;
;                         const bf16_t* up = U + (size_t)row * 1024 + col; const u32x4 z0 = {0u, 0u, 0u, 0u};
;                         const u32x4 uc = *(const u32x4*)up, ul = up_in ? *(const u32x4*)(up - 1024) : z0, ur = dn_in ? *(const u32x4*)(up + 1024) : z0;
;                         const f32x4 b0 = acc[ai][bj][m][0] * r, b1 = acc[ai][bj][m][1] * r;
;                         u32x4 w;
;                         w.x = cvt_pk_bf16(b0[0] * (k0a[0] * bf_lo(ul.x) + k1a[0] * bf_lo(uc.x) + k2a[0] * bf_lo(ur.x)), b0[1] * (k0a[1] * bf_hi(ul.x) + k1a[1] * bf_hi(uc.x) + k2a[1] * bf_hi(ur.x)));
;                         w.y = cvt_pk_bf16(b0[2] * (k0a[2] * bf_lo(ul.y) + k1a[2] * bf_lo(uc.y) + k2a[2] * bf_lo(ur.y)), b0[3] * (k0a[3] * bf_hi(ul.y) + k1a[3] * bf_hi(uc.y) + k2a[3] * bf_hi(ur.y)));
;                         w.z = cvt_pk_bf16(b1[0] * (k0b[0] * bf_lo(ul.z) + k1b[0] * bf_lo(uc.z) + k2b[0] * bf_lo(ur.z)), b1[1] * (k0b[1] * bf_hi(ul.z) + k1b[1] * bf_hi(uc.z) + k2b[1] * bf_hi(ur.z)));
;                         w.w = cvt_pk_bf16(b1[2] * (k0b[2] * bf_lo(ul.w) + k1b[2] * bf_lo(uc.w) + k2b[2] * bf_lo(ur.w)), b1[3] * (k0b[3] * bf_hi(ul.w) + k1b[3] * bf_hi(uc.w) + k2b[3] * bf_hi(ur.w)));
;                         if (up_halo || dn_halo) { const size_t ho = (size_t)(2 * u.pm + (dn_halo ? 1 : 0)) * 1024 + col;
;                             u32x4 bw; bw.x = cvt_pk_bf16(b0[0], b0[1]); bw.y = cvt_pk_bf16(b0[2], b0[3]); bw.z = cvt_pk_bf16(b1[0], b1[1]); bw.w = cvt_pk_bf16(b1[2], b1[3]);
;                             *(u32x4*)(HZ + ho) = w; *(u32x4*)(HBg + ho) = bw; }
;                         else *(u32x4*)(Z + (size_t)row * 1024 + col) = w; }
.LBB0_344:
	s_or_b64 exec, exec, s[78:79]
	v_lshlrev_b64 v[240:241], 10, v[228:229]
	v_and_b32_e32 v168, 0x1fff, v228
	s_waitcnt lgkmcnt(0)
	v_lshlrev_b32_e32 v228, 16, v162
	v_and_b32_e32 v229, 0xffff0000, v162
	v_lshlrev_b32_e32 v162, 16, v163
	v_and_b32_e32 v163, 0xffff0000, v163
	v_lshlrev_b32_e32 v246, 16, v158
	v_and_b32_e32 v247, 0xffff0000, v158
	v_pk_mul_f32 v[162:163], v[152:153], v[162:163]
	v_lshlrev_b32_e32 v158, 16, v159
	v_and_b32_e32 v159, 0xffff0000, v159
	v_pk_fma_f32 v[158:159], v[148:149], v[158:159], v[162:163]
	v_lshlrev_b32_e32 v162, 16, v155
	v_and_b32_e32 v163, 0xffff0000, v155
	v_pk_mul_f32 v[232:233], v[32:33], v[186:187] op_sel_hi:[1,0]
	v_pk_fma_f32 v[158:159], v[144:145], v[162:163], v[158:159]
	v_lshlrev_b32_e32 v162, 16, v160
	v_pk_mul_f32 v[158:159], v[232:233], v[158:159]
	v_and_b32_e32 v163, 0xffff0000, v160
	v_cvt_pk_bf16_f32 v155, v158, v159
	v_lshlrev_b32_e32 v158, 16, v164
	v_and_b32_e32 v159, 0xffff0000, v164
	v_pk_mul_f32 v[158:159], v[130:131], v[158:159]
	v_pk_mul_f32 v[238:239], v[22:23], v[186:187] op_sel_hi:[1,0]
	v_pk_fma_f32 v[158:159], v[134:135], v[162:163], v[158:159]
	v_lshlrev_b32_e32 v162, 16, v156
	v_and_b32_e32 v163, 0xffff0000, v156
	v_pk_fma_f32 v[158:159], v[138:139], v[162:163], v[158:159]
	v_pk_mul_f32 v[228:229], v[150:151], v[228:229]
	v_pk_mul_f32 v[158:159], v[238:239], v[158:159]
	v_lshlrev_b32_e32 v160, 16, v161
	v_cvt_pk_bf16_f32 v156, v158, v159
	v_lshlrev_b32_e32 v158, 16, v165
	v_and_b32_e32 v159, 0xffff0000, v165
	v_pk_mul_f32 v[158:159], v[132:133], v[158:159]
	v_and_b32_e32 v161, 0xffff0000, v161
	v_cmp_ne_u32_e32 vcc, 0, v168
	s_movk_i32 s38, 0x1fff
	v_pk_fma_f32 v[228:229], v[146:147], v[246:247], v[228:229]
	v_lshlrev_b32_e32 v246, 16, v154
	v_and_b32_e32 v247, 0xffff0000, v154
	v_pk_fma_f32 v[158:159], v[136:137], v[160:161], v[158:159]
	v_lshlrev_b32_e32 v160, 16, v157
	v_and_b32_e32 v161, 0xffff0000, v157
	s_and_b64 s[78:79], s[56:57], vcc
	v_cmp_ne_u32_e32 vcc, s38, v168
	v_pk_mul_f32 v[234:235], v[30:31], v[186:187] op_sel_hi:[1,0]
	v_pk_mul_f32 v[236:237], v[24:25], v[186:187] op_sel_hi:[1,0]
	v_pk_fma_f32 v[228:229], v[142:143], v[246:247], v[228:229]
	v_pk_fma_f32 v[158:159], v[140:141], v[160:161], v[158:159]
	s_and_b64 s[56:57], s[60:61], vcc
	v_pk_mul_f32 v[228:229], v[234:235], v[228:229]
	v_pk_mul_f32 v[158:159], v[236:237], v[158:159]
	v_cvt_pk_bf16_f32 v154, v228, v229
	v_cvt_pk_bf16_f32 v157, v158, v159
	s_nor_b64 s[88:89], s[78:79], s[56:57]
	v_lshl_add_u64 v[228:229], v[240:241], 1, s[74:75]
	s_and_saveexec_b64 s[60:61], s[88:89]
	s_xor_b64 s[60:61], exec, s[60:61]
	s_cbranch_execz .LBB0_346
	v_lshl_add_u64 v[158:159], v[206:207], 1, v[228:229]
	v_subrev_u32_e32 v172, s74, v158
	v_bfe_u32 v174, v172, 4, 7
	v_lshrrev_b32_e32 v172, 11, v172
	v_lshlrev_b32_e32 v174, 18, v174
	v_lshl_or_b32 v172, v172, 4, v174
	v_mov_b32_e32 v173, 0
	v_lshl_add_u64 v[172:173], s[74:75], 0, v[172:173]
	global_store_dwordx4 v[172:173], v[154:157], off

; __device__ __forceinline__ unsigned cvt_pk_bf16(float lo, float hi) { f32x2_t v = {lo, hi}; bf16x2_t b = __builtin_convertvector(v, bf16x2_t); return __builtin_bit_cast(unsigned, b); }
;     __device__ __forceinline__ void operator()(const f32x4 (&acc)[2][2][4][2], const Unit& u, int wr, int wc, int fr, int fq) const {
;     ...
;                     for (int m = 0; m < 4; ++m) { const int row = row0 + ai * HALF + m * 16, sq = row & 8191, lr = row & 255; const float r = rr[ai][m];
;                         const bool up_in = lr != 0, dn_in = lr != 255, up_halo = !up_in && sq != 0, dn_halo = !dn_in && sq != 8191;
;                         const bf16_t* up = U + (size_t)row * 1024 + col; const u32x4 z0 = {0u, 0u, 0u, 0u};
;                         const u32x4 uc = *(const u32x4*)up, ul = up_in ? *(const u32x4*)(up - 1024) : z0, ur = dn_in ? *(const u32x4*)(up + 1024) : z0;
;                         const f32x4 b0 = acc[ai][bj][m][0] * r, b1 = acc[ai][bj][m][1] * r;
;                         u32x4 w;
;                         w.x = cvt_pk_bf16(b0[0] * (k0a[0] * bf_lo(ul.x) + k1a[0] * bf_lo(uc.x) + k2a[0] * bf_lo(ur.x)), b0[1] * (k0a[1] * bf_hi(ul.x) + k1a[1] * bf_hi(uc.x) + k2a[1] * bf_hi(ur.x)));
;                         w.y = cvt_pk_bf16(b0[2] * (k0a[2] * bf_lo(ul.y) + k1a[2] * bf_lo(uc.y) + k2a[2] * bf_lo(ur.y)), b0[3] * (k0a[3] * bf_hi(ul.y) + k1a[3] * bf_hi(uc.y) + k2a[3] * bf_hi(ur.y)));
;                         w.z = cvt_pk_bf16(b1[0] * (k0b[0] * bf_lo(ul.z) + k1b[0] * bf_lo(uc.z) + k2b[0] * bf_lo(ur.z)), b1[1] * (k0b[1] * bf_hi(ul.z) + k1b[1] * bf_hi(uc.z) + k2b[1] * bf_hi(ur.z)));
;                         w.w = cvt_pk_bf16(b1[2] * (k0b[2] * bf_lo(ul.w) + k1b[2] * bf_lo(uc.w) + k2b[2] * bf_lo(ur.w)), b1[3] * (k0b[3] * bf_hi(ul.w) + k1b[3] * bf_hi(uc.w) + k2b[3] * bf_hi(ur.w)));
;                         if (up_halo || dn_halo) { const size_t ho = (size_t)(2 * u.pm + (dn_halo ? 1 : 0)) * 1024 + col;
;                             u32x4 bw; bw.x = cvt_pk_bf16(b0[0], b0[1]); bw.y = cvt_pk_bf16(b0[2], b0[3]); bw.z = cvt_pk_bf16(b1[0], b1[1]); bw.w = cvt_pk_bf16(b1[2], b1[3]);
;                             *(u32x4*)(HZ + ho) = w; *(u32x4*)(HBg + ho) = bw; }
;                         else *(u32x4*)(Z + (size_t)row * 1024 + col) = w; }
.LBB0_352:
	s_or_b64 exec, exec, vcc
	v_lshlrev_b64 v[168:169], 10, v[202:203]
	v_and_b32_e32 v170, 0x1fff, v202
	s_waitcnt lgkmcnt(0)
	v_lshlrev_b32_e32 v202, 16, v162
	v_and_b32_e32 v203, 0xffff0000, v162
	v_pk_mul_f32 v[150:151], v[150:151], v[202:203]
	v_lshlrev_b32_e32 v202, 16, v158
	v_and_b32_e32 v203, 0xffff0000, v158
	v_pk_fma_f32 v[146:147], v[146:147], v[202:203], v[150:151]
	v_lshlrev_b32_e32 v150, 16, v154
	v_and_b32_e32 v151, 0xffff0000, v154
	v_pk_fma_f32 v[142:143], v[142:143], v[150:151], v[146:147]
	v_lshlrev_b32_e32 v146, 16, v163
	v_and_b32_e32 v147, 0xffff0000, v163
	v_pk_mul_f32 v[146:147], v[152:153], v[146:147]
	v_lshlrev_b32_e32 v150, 16, v159
	v_and_b32_e32 v151, 0xffff0000, v159
	v_pk_fma_f32 v[146:147], v[148:149], v[150:151], v[146:147]
	v_lshlrev_b32_e32 v148, 16, v155
	v_and_b32_e32 v149, 0xffff0000, v155
	v_pk_mul_f32 v[234:235], v[16:17], v[184:185] op_sel_hi:[1,0]
	v_pk_mul_f32 v[236:237], v[14:15], v[184:185] op_sel_hi:[1,0]
	v_pk_fma_f32 v[144:145], v[144:145], v[148:149], v[146:147]
	v_pk_mul_f32 v[142:143], v[236:237], v[142:143]
	v_pk_mul_f32 v[144:145], v[234:235], v[144:145]
	v_cvt_pk_bf16_f32 v142, v142, v143
	v_cvt_pk_bf16_f32 v143, v144, v145
	v_lshlrev_b32_e32 v144, 16, v164
	v_and_b32_e32 v145, 0xffff0000, v164
	v_pk_mul_f32 v[130:131], v[130:131], v[144:145]
	v_lshlrev_b32_e32 v144, 16, v160
	v_and_b32_e32 v145, 0xffff0000, v160
	v_pk_fma_f32 v[130:131], v[134:135], v[144:145], v[130:131]
	v_lshlrev_b32_e32 v134, 16, v156
	v_and_b32_e32 v135, 0xffff0000, v156
	v_pk_mul_f32 v[240:241], v[6:7], v[184:185] op_sel_hi:[1,0]
	v_pk_fma_f32 v[130:131], v[138:139], v[134:135], v[130:131]
	v_cmp_ne_u32_e32 vcc, 0, v170
	v_pk_mul_f32 v[130:131], v[240:241], v[130:131]
	s_and_b64 s[38:39], s[86:87], vcc
	v_cvt_pk_bf16_f32 v144, v130, v131
	v_lshlrev_b32_e32 v130, 16, v165
	v_and_b32_e32 v131, 0xffff0000, v165
	v_pk_mul_f32 v[130:131], v[132:133], v[130:131]
	v_lshlrev_b32_e32 v132, 16, v161
	v_and_b32_e32 v133, 0xffff0000, v161
	s_movk_i32 s86, 0x1fff
	v_pk_fma_f32 v[130:131], v[136:137], v[132:133], v[130:131]
	v_lshlrev_b32_e32 v132, 16, v157
	v_and_b32_e32 v133, 0xffff0000, v157
	v_cmp_ne_u32_e32 vcc, s86, v170
	v_pk_mul_f32 v[238:239], v[8:9], v[184:185] op_sel_hi:[1,0]
	v_pk_fma_f32 v[130:131], v[140:141], v[132:133], v[130:131]
	s_and_b64 s[86:87], s[78:79], vcc
	v_pk_mul_f32 v[130:131], v[238:239], v[130:131]
	s_nor_b64 vcc, s[38:39], s[86:87]
	v_cvt_pk_bf16_f32 v145, v130, v131
	v_lshl_add_u64 v[202:203], v[168:169], 1, s[74:75]
	s_and_saveexec_b64 s[38:39], vcc
	s_xor_b64 s[78:79], exec, s[38:39]
	s_cbranch_execz .LBB0_354
	v_lshl_add_u64 v[130:131], v[206:207], 1, v[202:203]
	v_subrev_u32_e32 v172, s74, v130
	v_bfe_u32 v174, v172, 4, 7
	v_lshrrev_b32_e32 v172, 11, v172
	v_lshlrev_b32_e32 v174, 18, v174
	v_lshl_or_b32 v172, v172, 4, v174
	v_mov_b32_e32 v173, 0
	v_lshl_add_u64 v[172:173], s[74:75], 0, v[172:173]
	global_store_dwordx4 v[172:173], v[142:145], off

; __device__ __forceinline__ unsigned cvt_pk_bf16(float lo, float hi) { f32x2_t v = {lo, hi}; bf16x2_t b = __builtin_convertvector(v, bf16x2_t); return __builtin_bit_cast(unsigned, b); }
;     __device__ __forceinline__ void operator()(const f32x4 (&acc)[2][2][4][2], const Unit& u, int wr, int wc, int fr, int fq) const {
;     ...
;                     for (int m = 0; m < 4; ++m) { const int row = row0 + ai * HALF + m * 16, sq = row & 8191, lr = row & 255; const float r = rr[ai][m];
;                         const bool up_in = lr != 0, dn_in = lr != 255, up_halo = !up_in && sq != 0, dn_halo = !dn_in && sq != 8191;
;                         const bf16_t* up = U + (size_t)row * 1024 + col; const u32x4 z0 = {0u, 0u, 0u, 0u};
;                         const u32x4 uc = *(const u32x4*)up, ul = up_in ? *(const u32x4*)(up - 1024) : z0, ur = dn_in ? *(const u32x4*)(up + 1024) : z0;
;                         const f32x4 b0 = acc[ai][bj][m][0] * r, b1 = acc[ai][bj][m][1] * r;
;                         u32x4 w;
;                         w.x = cvt_pk_bf16(b0[0] * (k0a[0] * bf_lo(ul.x) + k1a[0] * bf_lo(uc.x) + k2a[0] * bf_lo(ur.x)), b0[1] * (k0a[1] * bf_hi(ul.x) + k1a[1] * bf_hi(uc.x) + k2a[1] * bf_hi(ur.x)));
;                         w.y = cvt_pk_bf16(b0[2] * (k0a[2] * bf_lo(ul.y) + k1a[2] * bf_lo(uc.y) + k2a[2] * bf_lo(ur.y)), b0[3] * (k0a[3] * bf_hi(ul.y) + k1a[3] * bf_hi(uc.y) + k2a[3] * bf_hi(ur.y)));
;                         w.z = cvt_pk_bf16(b1[0] * (k0b[0] * bf_lo(ul.z) + k1b[0] * bf_lo(uc.z) + k2b[0] * bf_lo(ur.z)), b1[1] * (k0b[1] * bf_hi(ul.z) + k1b[1] * bf_hi(uc.z) + k2b[1] * bf_hi(ur.z)));
;                         w.w = cvt_pk_bf16(b1[2] * (k0b[2] * bf_lo(ul.w) + k1b[2] * bf_lo(uc.w) + k2b[2] * bf_lo(ur.w)), b1[3] * (k0b[3] * bf_hi(ul.w) + k1b[3] * bf_hi(uc.w) + k2b[3] * bf_hi(ur.w)));
;                         if (up_halo || dn_halo) { const size_t ho = (size_t)(2 * u.pm + (dn_halo ? 1 : 0)) * 1024 + col;
;                             u32x4 bw; bw.x = cvt_pk_bf16(b0[0], b0[1]); bw.y = cvt_pk_bf16(b0[2], b0[3]); bw.z = cvt_pk_bf16(b1[0], b1[1]); bw.w = cvt_pk_bf16(b1[2], b1[3]);
;                             *(u32x4*)(HZ + ho) = w; *(u32x4*)(HBg + ho) = bw; }
;                         else *(u32x4*)(Z + (size_t)row * 1024 + col) = w; }
.LBB0_360:
	s_or_b64 exec, exec, s[6:7]
	v_mov_b32_e32 v168, v198
	v_mov_b32_e32 v169, v198
	v_pk_mul_f32 v[234:235], v[128:129], v[168:169]
	v_pk_mul_f32 v[238:239], v[116:117], v[168:169]
	s_waitcnt lgkmcnt(0)
	v_lshlrev_b32_e32 v168, 16, v162
	v_and_b32_e32 v169, 0xffff0000, v162
	v_lshlrev_b32_e32 v162, 16, v163
	v_and_b32_e32 v163, 0xffff0000, v163
	v_lshlrev_b32_e32 v170, 16, v158
	v_and_b32_e32 v171, 0xffff0000, v158
	v_pk_mul_f32 v[162:163], v[152:153], v[162:163]
	v_lshlrev_b32_e32 v158, 16, v159
	v_and_b32_e32 v159, 0xffff0000, v159
	v_pk_fma_f32 v[158:159], v[148:149], v[158:159], v[162:163]
	v_lshlrev_b32_e32 v162, 16, v155
	v_and_b32_e32 v163, 0xffff0000, v155
	v_pk_fma_f32 v[158:159], v[144:145], v[162:163], v[158:159]
	v_lshlrev_b32_e32 v162, 16, v160
	v_pk_mul_f32 v[158:159], v[234:235], v[158:159]
	v_and_b32_e32 v163, 0xffff0000, v160
	v_cvt_pk_bf16_f32 v155, v158, v159
	v_lshlrev_b32_e32 v158, 16, v164
	v_and_b32_e32 v159, 0xffff0000, v164
	v_pk_mul_f32 v[158:159], v[130:131], v[158:159]
	v_mov_b32_e32 v199, v198
	v_pk_fma_f32 v[158:159], v[134:135], v[162:163], v[158:159]
	v_lshlrev_b32_e32 v162, 16, v156
	v_and_b32_e32 v163, 0xffff0000, v156
	v_pk_mul_f32 v[240:241], v[114:115], v[198:199]
	v_pk_fma_f32 v[158:159], v[138:139], v[162:163], v[158:159]
	v_pk_mul_f32 v[168:169], v[150:151], v[168:169]
	v_pk_mul_f32 v[158:159], v[240:241], v[158:159]
	v_lshlrev_b32_e32 v160, 16, v161
	v_cvt_pk_bf16_f32 v156, v158, v159
	v_lshlrev_b32_e32 v158, 16, v165
	v_and_b32_e32 v159, 0xffff0000, v165
	v_pk_mul_f32 v[158:159], v[132:133], v[158:159]
	v_and_b32_e32 v161, 0xffff0000, v161
	v_pk_fma_f32 v[168:169], v[146:147], v[170:171], v[168:169]
	v_lshlrev_b32_e32 v170, 16, v154
	v_and_b32_e32 v171, 0xffff0000, v154
	v_pk_fma_f32 v[158:159], v[136:137], v[160:161], v[158:159]
	v_lshlrev_b32_e32 v160, 16, v157
	v_and_b32_e32 v161, 0xffff0000, v157
	v_pk_mul_f32 v[236:237], v[126:127], v[198:199]
	v_pk_fma_f32 v[168:169], v[142:143], v[170:171], v[168:169]
	v_pk_fma_f32 v[158:159], v[140:141], v[160:161], v[158:159]
	v_pk_mul_f32 v[168:169], v[236:237], v[168:169]
	v_pk_mul_f32 v[158:159], v[238:239], v[158:159]
	v_cvt_pk_bf16_f32 v154, v168, v169
	v_cvt_pk_bf16_f32 v157, v158, v159
	s_and_saveexec_b64 s[6:7], s[10:11]
	s_xor_b64 s[6:7], exec, s[6:7]
	s_cbranch_execz .LBB0_362
	v_lshl_add_u64 v[158:159], v[206:207], 1, v[204:205]
	v_subrev_u32_e32 v172, s74, v158
	v_bfe_u32 v174, v172, 4, 7
	v_lshrrev_b32_e32 v172, 11, v172
	v_lshlrev_b32_e32 v174, 18, v174
	v_lshl_or_b32 v172, v172, 4, v174
	v_mov_b32_e32 v173, 0
	v_lshl_add_u64 v[172:173], s[74:75], 0, v[172:173]
	global_store_dwordx4 v[172:173], v[154:157], off

; __device__ __forceinline__ unsigned cvt_pk_bf16(float lo, float hi) { f32x2_t v = {lo, hi}; bf16x2_t b = __builtin_convertvector(v, bf16x2_t); return __builtin_bit_cast(unsigned, b); }
;     __device__ __forceinline__ void operator()(const f32x4 (&acc)[2][2][4][2], const Unit& u, int wr, int wc, int fr, int fq) const {
;     ...
;                     for (int m = 0; m < 4; ++m) { const int row = row0 + ai * HALF + m * 16, sq = row & 8191, lr = row & 255; const float r = rr[ai][m];
;                         const bool up_in = lr != 0, dn_in = lr != 255, up_halo = !up_in && sq != 0, dn_halo = !dn_in && sq != 8191;
;                         const bf16_t* up = U + (size_t)row * 1024 + col; const u32x4 z0 = {0u, 0u, 0u, 0u};
;                         const u32x4 uc = *(const u32x4*)up, ul = up_in ? *(const u32x4*)(up - 1024) : z0, ur = dn_in ? *(const u32x4*)(up + 1024) : z0;
;                         const f32x4 b0 = acc[ai][bj][m][0] * r, b1 = acc[ai][bj][m][1] * r;
;                         u32x4 w;
;                         w.x = cvt_pk_bf16(b0[0] * (k0a[0] * bf_lo(ul.x) + k1a[0] * bf_lo(uc.x) + k2a[0] * bf_lo(ur.x)), b0[1] * (k0a[1] * bf_hi(ul.x) + k1a[1] * bf_hi(uc.x) + k2a[1] * bf_hi(ur.x)));
;                         w.y = cvt_pk_bf16(b0[2] * (k0a[2] * bf_lo(ul.y) + k1a[2] * bf_lo(uc.y) + k2a[2] * bf_lo(ur.y)), b0[3] * (k0a[3] * bf_hi(ul.y) + k1a[3] * bf_hi(uc.y) + k2a[3] * bf_hi(ur.y)));
;                         w.z = cvt_pk_bf16(b1[0] * (k0b[0] * bf_lo(ul.z) + k1b[0] * bf_lo(uc.z) + k2b[0] * bf_lo(ur.z)), b1[1] * (k0b[1] * bf_hi(ul.z) + k1b[1] * bf_hi(uc.z) + k2b[1] * bf_hi(ur.z)));
;                         w.w = cvt_pk_bf16(b1[2] * (k0b[2] * bf_lo(ul.w) + k1b[2] * bf_lo(uc.w) + k2b[2] * bf_lo(ur.w)), b1[3] * (k0b[3] * bf_hi(ul.w) + k1b[3] * bf_hi(uc.w) + k2b[3] * bf_hi(ur.w)));
;                         if (up_halo || dn_halo) { const size_t ho = (size_t)(2 * u.pm + (dn_halo ? 1 : 0)) * 1024 + col;
;                             u32x4 bw; bw.x = cvt_pk_bf16(b0[0], b0[1]); bw.y = cvt_pk_bf16(b0[2], b0[3]); bw.z = cvt_pk_bf16(b1[0], b1[1]); bw.w = cvt_pk_bf16(b1[2], b1[3]);
;                             *(u32x4*)(HZ + ho) = w; *(u32x4*)(HBg + ho) = bw; }
;                         else *(u32x4*)(Z + (size_t)row * 1024 + col) = w; }
.LBB0_368:
	s_or_b64 exec, exec, s[6:7]
	v_mov_b32_e32 v168, v196
	v_mov_b32_e32 v169, v196
	v_pk_mul_f32 v[204:205], v[108:109], v[168:169]
	v_pk_mul_f32 v[234:235], v[100:101], v[168:169]
	s_waitcnt lgkmcnt(0)
	v_lshlrev_b32_e32 v168, 16, v162
	v_and_b32_e32 v169, 0xffff0000, v162
	v_lshlrev_b32_e32 v162, 16, v163
	v_and_b32_e32 v163, 0xffff0000, v163
	v_lshlrev_b32_e32 v170, 16, v158
	v_and_b32_e32 v171, 0xffff0000, v158
	v_pk_mul_f32 v[162:163], v[152:153], v[162:163]
	v_lshlrev_b32_e32 v158, 16, v159
	v_and_b32_e32 v159, 0xffff0000, v159
	v_pk_fma_f32 v[158:159], v[148:149], v[158:159], v[162:163]
	v_lshlrev_b32_e32 v162, 16, v155
	v_and_b32_e32 v163, 0xffff0000, v155
	v_pk_fma_f32 v[158:159], v[144:145], v[162:163], v[158:159]
	v_lshlrev_b32_e32 v162, 16, v160
	v_pk_mul_f32 v[158:159], v[204:205], v[158:159]
	v_and_b32_e32 v163, 0xffff0000, v160
	v_cvt_pk_bf16_f32 v155, v158, v159
	v_lshlrev_b32_e32 v158, 16, v164
	v_and_b32_e32 v159, 0xffff0000, v164
	v_pk_mul_f32 v[158:159], v[130:131], v[158:159]
	v_mov_b32_e32 v197, v196
	v_pk_fma_f32 v[158:159], v[134:135], v[162:163], v[158:159]
	v_lshlrev_b32_e32 v162, 16, v156
	v_and_b32_e32 v163, 0xffff0000, v156
	v_pk_mul_f32 v[236:237], v[98:99], v[196:197]
	v_pk_fma_f32 v[158:159], v[138:139], v[162:163], v[158:159]
	v_pk_mul_f32 v[168:169], v[150:151], v[168:169]
	v_pk_mul_f32 v[158:159], v[236:237], v[158:159]
	v_lshlrev_b32_e32 v160, 16, v161
	v_cvt_pk_bf16_f32 v156, v158, v159
	v_lshlrev_b32_e32 v158, 16, v165
	v_and_b32_e32 v159, 0xffff0000, v165
	v_pk_mul_f32 v[158:159], v[132:133], v[158:159]
	v_and_b32_e32 v161, 0xffff0000, v161
	v_pk_fma_f32 v[168:169], v[146:147], v[170:171], v[168:169]
	v_lshlrev_b32_e32 v170, 16, v154
	v_and_b32_e32 v171, 0xffff0000, v154
	v_pk_fma_f32 v[158:159], v[136:137], v[160:161], v[158:159]
	v_lshlrev_b32_e32 v160, 16, v157
	v_and_b32_e32 v161, 0xffff0000, v157
	v_pk_mul_f32 v[210:211], v[106:107], v[196:197]
	v_pk_fma_f32 v[168:169], v[142:143], v[170:171], v[168:169]
	v_pk_fma_f32 v[158:159], v[140:141], v[160:161], v[158:159]
	v_pk_mul_f32 v[168:169], v[210:211], v[168:169]
	v_pk_mul_f32 v[158:159], v[234:235], v[158:159]
	v_cvt_pk_bf16_f32 v154, v168, v169
	v_cvt_pk_bf16_f32 v157, v158, v159
	s_and_saveexec_b64 s[6:7], s[16:17]
	s_xor_b64 s[6:7], exec, s[6:7]
	s_cbranch_execz .LBB0_370
	v_lshl_add_u64 v[158:159], v[206:207], 1, v[208:209]
	v_subrev_u32_e32 v172, s74, v158
	v_bfe_u32 v174, v172, 4, 7
	v_lshrrev_b32_e32 v172, 11, v172
	v_lshlrev_b32_e32 v174, 18, v174
	v_lshl_or_b32 v172, v172, 4, v174
	v_mov_b32_e32 v173, 0
	v_lshl_add_u64 v[172:173], s[74:75], 0, v[172:173]
	global_store_dwordx4 v[172:173], v[154:157], off

; __device__ __forceinline__ unsigned cvt_pk_bf16(float lo, float hi) { f32x2_t v = {lo, hi}; bf16x2_t b = __builtin_convertvector(v, bf16x2_t); return __builtin_bit_cast(unsigned, b); }
;     __device__ __forceinline__ void operator()(const f32x4 (&acc)[2][2][4][2], const Unit& u, int wr, int wc, int fr, int fq) const {
;     ...
;                     for (int m = 0; m < 4; ++m) { const int row = row0 + ai * HALF + m * 16, sq = row & 8191, lr = row & 255; const float r = rr[ai][m];
;                         const bool up_in = lr != 0, dn_in = lr != 255, up_halo = !up_in && sq != 0, dn_halo = !dn_in && sq != 8191;
;                         const bf16_t* up = U + (size_t)row * 1024 + col; const u32x4 z0 = {0u, 0u, 0u, 0u};
;                         const u32x4 uc = *(const u32x4*)up, ul = up_in ? *(const u32x4*)(up - 1024) : z0, ur = dn_in ? *(const u32x4*)(up + 1024) : z0;
;                         const f32x4 b0 = acc[ai][bj][m][0] * r, b1 = acc[ai][bj][m][1] * r;
;                         u32x4 w;
;                         w.x = cvt_pk_bf16(b0[0] * (k0a[0] * bf_lo(ul.x) + k1a[0] * bf_lo(uc.x) + k2a[0] * bf_lo(ur.x)), b0[1] * (k0a[1] * bf_hi(ul.x) + k1a[1] * bf_hi(uc.x) + k2a[1] * bf_hi(ur.x)));
;                         w.y = cvt_pk_bf16(b0[2] * (k0a[2] * bf_lo(ul.y) + k1a[2] * bf_lo(uc.y) + k2a[2] * bf_lo(ur.y)), b0[3] * (k0a[3] * bf_hi(ul.y) + k1a[3] * bf_hi(uc.y) + k2a[3] * bf_hi(ur.y)));
;                         w.z = cvt_pk_bf16(b1[0] * (k0b[0] * bf_lo(ul.z) + k1b[0] * bf_lo(uc.z) + k2b[0] * bf_lo(ur.z)), b1[1] * (k0b[1] * bf_hi(ul.z) + k1b[1] * bf_hi(uc.z) + k2b[1] * bf_hi(ur.z)));
;                         w.w = cvt_pk_bf16(b1[2] * (k0b[2] * bf_lo(ul.w) + k1b[2] * bf_lo(uc.w) + k2b[2] * bf_lo(ur.w)), b1[3] * (k0b[3] * bf_hi(ul.w) + k1b[3] * bf_hi(uc.w) + k2b[3] * bf_hi(ur.w)));
;                         if (up_halo || dn_halo) { const size_t ho = (size_t)(2 * u.pm + (dn_halo ? 1 : 0)) * 1024 + col;
;                             u32x4 bw; bw.x = cvt_pk_bf16(b0[0], b0[1]); bw.y = cvt_pk_bf16(b0[2], b0[3]); bw.z = cvt_pk_bf16(b1[0], b1[1]); bw.w = cvt_pk_bf16(b1[2], b1[3]);
;                             *(u32x4*)(HZ + ho) = w; *(u32x4*)(HBg + ho) = bw; }
;                         else *(u32x4*)(Z + (size_t)row * 1024 + col) = w; }
.LBB0_376:
	s_or_b64 exec, exec, s[6:7]
	v_mov_b32_e32 v168, v192
	v_mov_b32_e32 v169, v192
	v_pk_mul_f32 v[204:205], v[92:93], v[168:169]
	v_pk_mul_f32 v[210:211], v[84:85], v[168:169]
	s_waitcnt lgkmcnt(0)
	v_lshlrev_b32_e32 v168, 16, v162
	v_and_b32_e32 v169, 0xffff0000, v162
	v_lshlrev_b32_e32 v162, 16, v163
	v_and_b32_e32 v163, 0xffff0000, v163
	v_lshlrev_b32_e32 v170, 16, v158
	v_and_b32_e32 v171, 0xffff0000, v158
	v_pk_mul_f32 v[162:163], v[152:153], v[162:163]
	v_lshlrev_b32_e32 v158, 16, v159
	v_and_b32_e32 v159, 0xffff0000, v159
	v_pk_fma_f32 v[158:159], v[148:149], v[158:159], v[162:163]
	v_lshlrev_b32_e32 v162, 16, v155
	v_and_b32_e32 v163, 0xffff0000, v155
	v_pk_fma_f32 v[158:159], v[144:145], v[162:163], v[158:159]
	v_lshlrev_b32_e32 v162, 16, v160
	v_pk_mul_f32 v[158:159], v[204:205], v[158:159]
	v_and_b32_e32 v163, 0xffff0000, v160
	v_cvt_pk_bf16_f32 v155, v158, v159
	v_lshlrev_b32_e32 v158, 16, v164
	v_and_b32_e32 v159, 0xffff0000, v164
	v_pk_mul_f32 v[158:159], v[130:131], v[158:159]
	v_mov_b32_e32 v193, v192
	v_pk_fma_f32 v[158:159], v[134:135], v[162:163], v[158:159]
	v_lshlrev_b32_e32 v162, 16, v156
	v_and_b32_e32 v163, 0xffff0000, v156
	v_pk_mul_f32 v[214:215], v[82:83], v[192:193]
	v_pk_fma_f32 v[158:159], v[138:139], v[162:163], v[158:159]
	v_pk_mul_f32 v[168:169], v[150:151], v[168:169]
	v_pk_mul_f32 v[158:159], v[214:215], v[158:159]
	v_lshlrev_b32_e32 v160, 16, v161
	v_cvt_pk_bf16_f32 v156, v158, v159
	v_lshlrev_b32_e32 v158, 16, v165
	v_and_b32_e32 v159, 0xffff0000, v165
	v_pk_mul_f32 v[158:159], v[132:133], v[158:159]
	v_and_b32_e32 v161, 0xffff0000, v161
	v_pk_fma_f32 v[168:169], v[146:147], v[170:171], v[168:169]
	v_lshlrev_b32_e32 v170, 16, v154
	v_and_b32_e32 v171, 0xffff0000, v154
	v_pk_fma_f32 v[158:159], v[136:137], v[160:161], v[158:159]
	v_lshlrev_b32_e32 v160, 16, v157
	v_and_b32_e32 v161, 0xffff0000, v157
	v_pk_mul_f32 v[208:209], v[90:91], v[192:193]
	v_pk_fma_f32 v[168:169], v[142:143], v[170:171], v[168:169]
	v_pk_fma_f32 v[158:159], v[140:141], v[160:161], v[158:159]
	v_pk_mul_f32 v[168:169], v[208:209], v[168:169]
	v_pk_mul_f32 v[158:159], v[210:211], v[158:159]
	v_cvt_pk_bf16_f32 v154, v168, v169
	v_cvt_pk_bf16_f32 v157, v158, v159
	s_and_saveexec_b64 s[6:7], s[22:23]
	s_xor_b64 s[6:7], exec, s[6:7]
	s_cbranch_execz .LBB0_378
	v_lshl_add_u64 v[158:159], v[206:207], 1, v[212:213]
	v_subrev_u32_e32 v172, s74, v158
	v_bfe_u32 v174, v172, 4, 7
	v_lshrrev_b32_e32 v172, 11, v172
	v_lshlrev_b32_e32 v174, 18, v174
	v_lshl_or_b32 v172, v172, 4, v174
	v_mov_b32_e32 v173, 0
	v_lshl_add_u64 v[172:173], s[74:75], 0, v[172:173]
	global_store_dwordx4 v[172:173], v[154:157], off

; __device__ __forceinline__ unsigned cvt_pk_bf16(float lo, float hi) { f32x2_t v = {lo, hi}; bf16x2_t b = __builtin_convertvector(v, bf16x2_t); return __builtin_bit_cast(unsigned, b); }
;     __device__ __forceinline__ void operator()(const f32x4 (&acc)[2][2][4][2], const Unit& u, int wr, int wc, int fr, int fq) const {
;     ...
;                     for (int m = 0; m < 4; ++m) { const int row = row0 + ai * HALF + m * 16, sq = row & 8191, lr = row & 255; const float r = rr[ai][m];
;                         const bool up_in = lr != 0, dn_in = lr != 255, up_halo = !up_in && sq != 0, dn_halo = !dn_in && sq != 8191;
;                         const bf16_t* up = U + (size_t)row * 1024 + col; const u32x4 z0 = {0u, 0u, 0u, 0u};
;                         const u32x4 uc = *(const u32x4*)up, ul = up_in ? *(const u32x4*)(up - 1024) : z0, ur = dn_in ? *(const u32x4*)(up + 1024) : z0;
;                         const f32x4 b0 = acc[ai][bj][m][0] * r, b1 = acc[ai][bj][m][1] * r;
;                         u32x4 w;
;                         w.x = cvt_pk_bf16(b0[0] * (k0a[0] * bf_lo(ul.x) + k1a[0] * bf_lo(uc.x) + k2a[0] * bf_lo(ur.x)), b0[1] * (k0a[1] * bf_hi(ul.x) + k1a[1] * bf_hi(uc.x) + k2a[1] * bf_hi(ur.x)));
;                         w.y = cvt_pk_bf16(b0[2] * (k0a[2] * bf_lo(ul.y) + k1a[2] * bf_lo(uc.y) + k2a[2] * bf_lo(ur.y)), b0[3] * (k0a[3] * bf_hi(ul.y) + k1a[3] * bf_hi(uc.y) + k2a[3] * bf_hi(ur.y)));
;                         w.z = cvt_pk_bf16(b1[0] * (k0b[0] * bf_lo(ul.z) + k1b[0] * bf_lo(uc.z) + k2b[0] * bf_lo(ur.z)), b1[1] * (k0b[1] * bf_hi(ul.z) + k1b[1] * bf_hi(uc.z) + k2b[1] * bf_hi(ur.z)));
;                         w.w = cvt_pk_bf16(b1[2] * (k0b[2] * bf_lo(ul.w) + k1b[2] * bf_lo(uc.w) + k2b[2] * bf_lo(ur.w)), b1[3] * (k0b[3] * bf_hi(ul.w) + k1b[3] * bf_hi(uc.w) + k2b[3] * bf_hi(ur.w)));
;                         if (up_halo || dn_halo) { const size_t ho = (size_t)(2 * u.pm + (dn_halo ? 1 : 0)) * 1024 + col;
;                             u32x4 bw; bw.x = cvt_pk_bf16(b0[0], b0[1]); bw.y = cvt_pk_bf16(b0[2], b0[3]); bw.z = cvt_pk_bf16(b1[0], b1[1]); bw.w = cvt_pk_bf16(b1[2], b1[3]);
;                             *(u32x4*)(HZ + ho) = w; *(u32x4*)(HBg + ho) = bw; }
;                         else *(u32x4*)(Z + (size_t)row * 1024 + col) = w; }
.LBB0_384:
	s_or_b64 exec, exec, s[6:7]
	v_mov_b32_e32 v168, v194
	v_mov_b32_e32 v169, v194
	v_pk_mul_f32 v[204:205], v[76:77], v[168:169]
	v_pk_mul_f32 v[210:211], v[68:69], v[168:169]
	s_waitcnt lgkmcnt(0)
	v_lshlrev_b32_e32 v168, 16, v162
	v_and_b32_e32 v169, 0xffff0000, v162
	v_lshlrev_b32_e32 v162, 16, v163
	v_and_b32_e32 v163, 0xffff0000, v163
	v_lshlrev_b32_e32 v170, 16, v158
	v_and_b32_e32 v171, 0xffff0000, v158
	v_pk_mul_f32 v[162:163], v[152:153], v[162:163]
	v_lshlrev_b32_e32 v158, 16, v159
	v_and_b32_e32 v159, 0xffff0000, v159
	v_pk_fma_f32 v[158:159], v[148:149], v[158:159], v[162:163]
	v_lshlrev_b32_e32 v162, 16, v155
	v_and_b32_e32 v163, 0xffff0000, v155
	v_pk_fma_f32 v[158:159], v[144:145], v[162:163], v[158:159]
	v_lshlrev_b32_e32 v162, 16, v160
	v_pk_mul_f32 v[158:159], v[204:205], v[158:159]
	v_and_b32_e32 v163, 0xffff0000, v160
	v_cvt_pk_bf16_f32 v155, v158, v159
	v_lshlrev_b32_e32 v158, 16, v164
	v_and_b32_e32 v159, 0xffff0000, v164
	v_pk_mul_f32 v[158:159], v[130:131], v[158:159]
	v_mov_b32_e32 v195, v194
	v_pk_fma_f32 v[158:159], v[134:135], v[162:163], v[158:159]
	v_lshlrev_b32_e32 v162, 16, v156
	v_and_b32_e32 v163, 0xffff0000, v156
	v_pk_mul_f32 v[212:213], v[66:67], v[194:195]
	v_pk_fma_f32 v[158:159], v[138:139], v[162:163], v[158:159]
	v_pk_mul_f32 v[168:169], v[150:151], v[168:169]
	v_pk_mul_f32 v[158:159], v[212:213], v[158:159]
	v_lshlrev_b32_e32 v160, 16, v161
	v_cvt_pk_bf16_f32 v156, v158, v159
	v_lshlrev_b32_e32 v158, 16, v165
	v_and_b32_e32 v159, 0xffff0000, v165
	v_pk_mul_f32 v[158:159], v[132:133], v[158:159]
	v_and_b32_e32 v161, 0xffff0000, v161
	v_pk_fma_f32 v[168:169], v[146:147], v[170:171], v[168:169]
	v_lshlrev_b32_e32 v170, 16, v154
	v_and_b32_e32 v171, 0xffff0000, v154
	v_pk_fma_f32 v[158:159], v[136:137], v[160:161], v[158:159]
	v_lshlrev_b32_e32 v160, 16, v157
	v_and_b32_e32 v161, 0xffff0000, v157
	v_pk_mul_f32 v[208:209], v[74:75], v[194:195]
	v_pk_fma_f32 v[168:169], v[142:143], v[170:171], v[168:169]
	v_pk_fma_f32 v[158:159], v[140:141], v[160:161], v[158:159]
	v_pk_mul_f32 v[168:169], v[208:209], v[168:169]
	v_pk_mul_f32 v[158:159], v[210:211], v[158:159]
	v_cvt_pk_bf16_f32 v154, v168, v169
	v_cvt_pk_bf16_f32 v157, v158, v159
	s_and_saveexec_b64 s[6:7], s[34:35]
	s_xor_b64 s[6:7], exec, s[6:7]
	s_cbranch_execz .LBB0_386
	v_lshl_add_u64 v[158:159], v[206:207], 1, v[216:217]
	v_subrev_u32_e32 v172, s74, v158
	v_bfe_u32 v174, v172, 4, 7
	v_lshrrev_b32_e32 v172, 11, v172
	v_lshlrev_b32_e32 v174, 18, v174
	v_lshl_or_b32 v172, v172, 4, v174
	v_mov_b32_e32 v173, 0
	v_lshl_add_u64 v[172:173], s[74:75], 0, v[172:173]
	global_store_dwordx4 v[172:173], v[154:157], off

; __device__ __forceinline__ unsigned cvt_pk_bf16(float lo, float hi) { f32x2_t v = {lo, hi}; bf16x2_t b = __builtin_convertvector(v, bf16x2_t); return __builtin_bit_cast(unsigned, b); }
;     __device__ __forceinline__ void operator()(const f32x4 (&acc)[2][2][4][2], const Unit& u, int wr, int wc, int fr, int fq) const {
;     ...
;                     for (int m = 0; m < 4; ++m) { const int row = row0 + ai * HALF + m * 16, sq = row & 8191, lr = row & 255; const float r = rr[ai][m];
;                         const bool up_in = lr != 0, dn_in = lr != 255, up_halo = !up_in && sq != 0, dn_halo = !dn_in && sq != 8191;
;                         const bf16_t* up = U + (size_t)row * 1024 + col; const u32x4 z0 = {0u, 0u, 0u, 0u};
;                         const u32x4 uc = *(const u32x4*)up, ul = up_in ? *(const u32x4*)(up - 1024) : z0, ur = dn_in ? *(const u32x4*)(up + 1024) : z0;
;                         const f32x4 b0 = acc[ai][bj][m][0] * r, b1 = acc[ai][bj][m][1] * r;
;                         u32x4 w;
;                         w.x = cvt_pk_bf16(b0[0] * (k0a[0] * bf_lo(ul.x) + k1a[0] * bf_lo(uc.x) + k2a[0] * bf_lo(ur.x)), b0[1] * (k0a[1] * bf_hi(ul.x) + k1a[1] * bf_hi(uc.x) + k2a[1] * bf_hi(ur.x)));
;                         w.y = cvt_pk_bf16(b0[2] * (k0a[2] * bf_lo(ul.y) + k1a[2] * bf_lo(uc.y) + k2a[2] * bf_lo(ur.y)), b0[3] * (k0a[3] * bf_hi(ul.y) + k1a[3] * bf_hi(uc.y) + k2a[3] * bf_hi(ur.y)));
;                         w.z = cvt_pk_bf16(b1[0] * (k0b[0] * bf_lo(ul.z) + k1b[0] * bf_lo(uc.z) + k2b[0] * bf_lo(ur.z)), b1[1] * (k0b[1] * bf_hi(ul.z) + k1b[1] * bf_hi(uc.z) + k2b[1] * bf_hi(ur.z)));
;                         w.w = cvt_pk_bf16(b1[2] * (k0b[2] * bf_lo(ul.w) + k1b[2] * bf_lo(uc.w) + k2b[2] * bf_lo(ur.w)), b1[3] * (k0b[3] * bf_hi(ul.w) + k1b[3] * bf_hi(uc.w) + k2b[3] * bf_hi(ur.w)));
;                         if (up_halo || dn_halo) { const size_t ho = (size_t)(2 * u.pm + (dn_halo ? 1 : 0)) * 1024 + col;
;                             u32x4 bw; bw.x = cvt_pk_bf16(b0[0], b0[1]); bw.y = cvt_pk_bf16(b0[2], b0[3]); bw.z = cvt_pk_bf16(b1[0], b1[1]); bw.w = cvt_pk_bf16(b1[2], b1[3]);
;                             *(u32x4*)(HZ + ho) = w; *(u32x4*)(HBg + ho) = bw; }
;                         else *(u32x4*)(Z + (size_t)row * 1024 + col) = w; }
.LBB0_392:
	s_or_b64 exec, exec, s[6:7]
	v_mov_b32_e32 v168, v190
	v_mov_b32_e32 v169, v190
	v_pk_mul_f32 v[204:205], v[60:61], v[168:169]
	v_pk_mul_f32 v[210:211], v[52:53], v[168:169]
	s_waitcnt lgkmcnt(0)
	v_lshlrev_b32_e32 v168, 16, v162
	v_and_b32_e32 v169, 0xffff0000, v162
	v_lshlrev_b32_e32 v162, 16, v163
	v_and_b32_e32 v163, 0xffff0000, v163
	v_lshlrev_b32_e32 v170, 16, v158
	v_and_b32_e32 v171, 0xffff0000, v158
	v_pk_mul_f32 v[162:163], v[152:153], v[162:163]
	v_lshlrev_b32_e32 v158, 16, v159
	v_and_b32_e32 v159, 0xffff0000, v159
	v_pk_fma_f32 v[158:159], v[148:149], v[158:159], v[162:163]
	v_lshlrev_b32_e32 v162, 16, v155
	v_and_b32_e32 v163, 0xffff0000, v155
	v_pk_fma_f32 v[158:159], v[144:145], v[162:163], v[158:159]
	v_lshlrev_b32_e32 v162, 16, v160
	v_pk_mul_f32 v[158:159], v[204:205], v[158:159]
	v_and_b32_e32 v163, 0xffff0000, v160
	v_cvt_pk_bf16_f32 v155, v158, v159
	v_lshlrev_b32_e32 v158, 16, v164
	v_and_b32_e32 v159, 0xffff0000, v164
	v_pk_mul_f32 v[158:159], v[130:131], v[158:159]
	v_mov_b32_e32 v191, v190
	v_pk_fma_f32 v[158:159], v[134:135], v[162:163], v[158:159]
	v_lshlrev_b32_e32 v162, 16, v156
	v_and_b32_e32 v163, 0xffff0000, v156
	v_pk_mul_f32 v[212:213], v[50:51], v[190:191]
	v_pk_fma_f32 v[158:159], v[138:139], v[162:163], v[158:159]
	v_pk_mul_f32 v[168:169], v[150:151], v[168:169]
	v_pk_mul_f32 v[158:159], v[212:213], v[158:159]
	v_lshlrev_b32_e32 v160, 16, v161
	v_cvt_pk_bf16_f32 v156, v158, v159
	v_lshlrev_b32_e32 v158, 16, v165
	v_and_b32_e32 v159, 0xffff0000, v165
	v_pk_mul_f32 v[158:159], v[132:133], v[158:159]
	v_and_b32_e32 v161, 0xffff0000, v161
	v_pk_fma_f32 v[168:169], v[146:147], v[170:171], v[168:169]
	v_lshlrev_b32_e32 v170, 16, v154
	v_and_b32_e32 v171, 0xffff0000, v154
	v_pk_fma_f32 v[158:159], v[136:137], v[160:161], v[158:159]
	v_lshlrev_b32_e32 v160, 16, v157
	v_and_b32_e32 v161, 0xffff0000, v157
	v_pk_mul_f32 v[208:209], v[58:59], v[190:191]
	v_pk_fma_f32 v[168:169], v[142:143], v[170:171], v[168:169]
	v_pk_fma_f32 v[158:159], v[140:141], v[160:161], v[158:159]
	v_pk_mul_f32 v[168:169], v[208:209], v[168:169]
	v_pk_mul_f32 v[158:159], v[210:211], v[158:159]
	v_cvt_pk_bf16_f32 v154, v168, v169
	v_cvt_pk_bf16_f32 v157, v158, v159
	s_and_saveexec_b64 s[6:7], s[44:45]
	s_xor_b64 s[6:7], exec, s[6:7]
	s_cbranch_execz .LBB0_394
	v_lshl_add_u64 v[158:159], v[206:207], 1, v[220:221]
	v_subrev_u32_e32 v172, s74, v158
	v_bfe_u32 v174, v172, 4, 7
	v_lshrrev_b32_e32 v172, 11, v172
	v_lshlrev_b32_e32 v174, 18, v174
	v_lshl_or_b32 v172, v172, 4, v174
	v_mov_b32_e32 v173, 0
	v_lshl_add_u64 v[172:173], s[74:75], 0, v[172:173]
	global_store_dwordx4 v[172:173], v[154:157], off

; __device__ __forceinline__ unsigned cvt_pk_bf16(float lo, float hi) { f32x2_t v = {lo, hi}; bf16x2_t b = __builtin_convertvector(v, bf16x2_t); return __builtin_bit_cast(unsigned, b); }
;     __device__ __forceinline__ void operator()(const f32x4 (&acc)[2][2][4][2], const Unit& u, int wr, int wc, int fr, int fq) const {
;     ...
;                     for (int m = 0; m < 4; ++m) { const int row = row0 + ai * HALF + m * 16, sq = row & 8191, lr = row & 255; const float r = rr[ai][m];
;                         const bool up_in = lr != 0, dn_in = lr != 255, up_halo = !up_in && sq != 0, dn_halo = !dn_in && sq != 8191;
;                         const bf16_t* up = U + (size_t)row * 1024 + col; const u32x4 z0 = {0u, 0u, 0u, 0u};
;                         const u32x4 uc = *(const u32x4*)up, ul = up_in ? *(const u32x4*)(up - 1024) : z0, ur = dn_in ? *(const u32x4*)(up + 1024) : z0;
;                         const f32x4 b0 = acc[ai][bj][m][0] * r, b1 = acc[ai][bj][m][1] * r;
;                         u32x4 w;
;                         w.x = cvt_pk_bf16(b0[0] * (k0a[0] * bf_lo(ul.x) + k1a[0] * bf_lo(uc.x) + k2a[0] * bf_lo(ur.x)), b0[1] * (k0a[1] * bf_hi(ul.x) + k1a[1] * bf_hi(uc.x) + k2a[1] * bf_hi(ur.x)));
;                         w.y = cvt_pk_bf16(b0[2] * (k0a[2] * bf_lo(ul.y) + k1a[2] * bf_lo(uc.y) + k2a[2] * bf_lo(ur.y)), b0[3] * (k0a[3] * bf_hi(ul.y) + k1a[3] * bf_hi(uc.y) + k2a[3] * bf_hi(ur.y)));
;                         w.z = cvt_pk_bf16(b1[0] * (k0b[0] * bf_lo(ul.z) + k1b[0] * bf_lo(uc.z) + k2b[0] * bf_lo(ur.z)), b1[1] * (k0b[1] * bf_hi(ul.z) + k1b[1] * bf_hi(uc.z) + k2b[1] * bf_hi(ur.z)));
;                         w.w = cvt_pk_bf16(b1[2] * (k0b[2] * bf_lo(ul.w) + k1b[2] * bf_lo(uc.w) + k2b[2] * bf_lo(ur.w)), b1[3] * (k0b[3] * bf_hi(ul.w) + k1b[3] * bf_hi(uc.w) + k2b[3] * bf_hi(ur.w)));
;                         if (up_halo || dn_halo) { const size_t ho = (size_t)(2 * u.pm + (dn_halo ? 1 : 0)) * 1024 + col;
;                             u32x4 bw; bw.x = cvt_pk_bf16(b0[0], b0[1]); bw.y = cvt_pk_bf16(b0[2], b0[3]); bw.z = cvt_pk_bf16(b1[0], b1[1]); bw.w = cvt_pk_bf16(b1[2], b1[3]);
;                             *(u32x4*)(HZ + ho) = w; *(u32x4*)(HBg + ho) = bw; }
;                         else *(u32x4*)(Z + (size_t)row * 1024 + col) = w; }
.LBB0_400:
	s_or_b64 exec, exec, s[6:7]
	v_mov_b32_e32 v168, v188
	v_mov_b32_e32 v169, v188
	v_pk_mul_f32 v[204:205], v[44:45], v[168:169]
	v_pk_mul_f32 v[210:211], v[36:37], v[168:169]
	s_waitcnt lgkmcnt(0)
	v_lshlrev_b32_e32 v168, 16, v162
	v_and_b32_e32 v169, 0xffff0000, v162
	v_lshlrev_b32_e32 v162, 16, v163
	v_and_b32_e32 v163, 0xffff0000, v163
	v_lshlrev_b32_e32 v170, 16, v158
	v_and_b32_e32 v171, 0xffff0000, v158
	v_pk_mul_f32 v[162:163], v[152:153], v[162:163]
	v_lshlrev_b32_e32 v158, 16, v159
	v_and_b32_e32 v159, 0xffff0000, v159
	v_pk_fma_f32 v[158:159], v[148:149], v[158:159], v[162:163]
	v_lshlrev_b32_e32 v162, 16, v155
	v_and_b32_e32 v163, 0xffff0000, v155
	v_pk_fma_f32 v[158:159], v[144:145], v[162:163], v[158:159]
	v_lshlrev_b32_e32 v162, 16, v160
	v_pk_mul_f32 v[158:159], v[204:205], v[158:159]
	v_and_b32_e32 v163, 0xffff0000, v160
	v_cvt_pk_bf16_f32 v155, v158, v159
	v_lshlrev_b32_e32 v158, 16, v164
	v_and_b32_e32 v159, 0xffff0000, v164
	v_pk_mul_f32 v[158:159], v[130:131], v[158:159]
	v_mov_b32_e32 v189, v188
	v_pk_fma_f32 v[158:159], v[134:135], v[162:163], v[158:159]
	v_lshlrev_b32_e32 v162, 16, v156
	v_and_b32_e32 v163, 0xffff0000, v156
	v_pk_mul_f32 v[212:213], v[34:35], v[188:189]
	v_pk_fma_f32 v[158:159], v[138:139], v[162:163], v[158:159]
	v_pk_mul_f32 v[168:169], v[150:151], v[168:169]
	v_pk_mul_f32 v[158:159], v[212:213], v[158:159]
	v_lshlrev_b32_e32 v160, 16, v161
	v_cvt_pk_bf16_f32 v156, v158, v159
	v_lshlrev_b32_e32 v158, 16, v165
	v_and_b32_e32 v159, 0xffff0000, v165
	v_pk_mul_f32 v[158:159], v[132:133], v[158:159]
	v_and_b32_e32 v161, 0xffff0000, v161
	v_pk_fma_f32 v[168:169], v[146:147], v[170:171], v[168:169]
	v_lshlrev_b32_e32 v170, 16, v154
	v_and_b32_e32 v171, 0xffff0000, v154
	v_pk_fma_f32 v[158:159], v[136:137], v[160:161], v[158:159]
	v_lshlrev_b32_e32 v160, 16, v157
	v_and_b32_e32 v161, 0xffff0000, v157
	v_pk_mul_f32 v[208:209], v[42:43], v[188:189]
	v_pk_fma_f32 v[168:169], v[142:143], v[170:171], v[168:169]
	v_pk_fma_f32 v[158:159], v[140:141], v[160:161], v[158:159]
	v_pk_mul_f32 v[168:169], v[208:209], v[168:169]
	v_pk_mul_f32 v[158:159], v[210:211], v[158:159]
	v_cvt_pk_bf16_f32 v154, v168, v169
	v_cvt_pk_bf16_f32 v157, v158, v159
	s_and_saveexec_b64 s[6:7], s[92:93]
	s_xor_b64 s[6:7], exec, s[6:7]
	s_cbranch_execz .LBB0_402
	v_lshl_add_u64 v[158:159], v[206:207], 1, v[224:225]
	v_subrev_u32_e32 v172, s74, v158
	v_bfe_u32 v174, v172, 4, 7
	v_lshrrev_b32_e32 v172, 11, v172
	v_lshlrev_b32_e32 v174, 18, v174
	v_lshl_or_b32 v172, v172, 4, v174
	v_mov_b32_e32 v173, 0
	v_lshl_add_u64 v[172:173], s[74:75], 0, v[172:173]
	global_store_dwordx4 v[172:173], v[154:157], off

; __device__ __forceinline__ unsigned cvt_pk_bf16(float lo, float hi) { f32x2_t v = {lo, hi}; bf16x2_t b = __builtin_convertvector(v, bf16x2_t); return __builtin_bit_cast(unsigned, b); }
;     __device__ __forceinline__ void operator()(const f32x4 (&acc)[2][2][4][2], const Unit& u, int wr, int wc, int fr, int fq) const {
;     ...
;                     for (int m = 0; m < 4; ++m) { const int row = row0 + ai * HALF + m * 16, sq = row & 8191, lr = row & 255; const float r = rr[ai][m];
;                         const bool up_in = lr != 0, dn_in = lr != 255, up_halo = !up_in && sq != 0, dn_halo = !dn_in && sq != 8191;
;                         const bf16_t* up = U + (size_t)row * 1024 + col; const u32x4 z0 = {0u, 0u, 0u, 0u};
;                         const u32x4 uc = *(const u32x4*)up, ul = up_in ? *(const u32x4*)(up - 1024) : z0, ur = dn_in ? *(const u32x4*)(up + 1024) : z0;
;                         const f32x4 b0 = acc[ai][bj][m][0] * r, b1 = acc[ai][bj][m][1] * r;
;                         u32x4 w;
;                         w.x = cvt_pk_bf16(b0[0] * (k0a[0] * bf_lo(ul.x) + k1a[0] * bf_lo(uc.x) + k2a[0] * bf_lo(ur.x)), b0[1] * (k0a[1] * bf_hi(ul.x) + k1a[1] * bf_hi(uc.x) + k2a[1] * bf_hi(ur.x)));
;                         w.y = cvt_pk_bf16(b0[2] * (k0a[2] * bf_lo(ul.y) + k1a[2] * bf_lo(uc.y) + k2a[2] * bf_lo(ur.y)), b0[3] * (k0a[3] * bf_hi(ul.y) + k1a[3] * bf_hi(uc.y) + k2a[3] * bf_hi(ur.y)));
;                         w.z = cvt_pk_bf16(b1[0] * (k0b[0] * bf_lo(ul.z) + k1b[0] * bf_lo(uc.z) + k2b[0] * bf_lo(ur.z)), b1[1] * (k0b[1] * bf_hi(ul.z) + k1b[1] * bf_hi(uc.z) + k2b[1] * bf_hi(ur.z)));
;                         w.w = cvt_pk_bf16(b1[2] * (k0b[2] * bf_lo(ul.w) + k1b[2] * bf_lo(uc.w) + k2b[2] * bf_lo(ur.w)), b1[3] * (k0b[3] * bf_hi(ul.w) + k1b[3] * bf_hi(uc.w) + k2b[3] * bf_hi(ur.w)));
;                         if (up_halo || dn_halo) { const size_t ho = (size_t)(2 * u.pm + (dn_halo ? 1 : 0)) * 1024 + col;
;                             u32x4 bw; bw.x = cvt_pk_bf16(b0[0], b0[1]); bw.y = cvt_pk_bf16(b0[2], b0[3]); bw.z = cvt_pk_bf16(b1[0], b1[1]); bw.w = cvt_pk_bf16(b1[2], b1[3]);
;                             *(u32x4*)(HZ + ho) = w; *(u32x4*)(HBg + ho) = bw; }
;                         else *(u32x4*)(Z + (size_t)row * 1024 + col) = w; }
.LBB0_408:
	s_or_b64 exec, exec, s[6:7]
	v_mov_b32_e32 v168, v186
	v_mov_b32_e32 v169, v186
	v_pk_mul_f32 v[204:205], v[28:29], v[168:169]
	v_pk_mul_f32 v[210:211], v[20:21], v[168:169]
	s_waitcnt lgkmcnt(0)
	v_lshlrev_b32_e32 v168, 16, v162
	v_and_b32_e32 v169, 0xffff0000, v162
	v_lshlrev_b32_e32 v162, 16, v163
	v_and_b32_e32 v163, 0xffff0000, v163
	v_lshlrev_b32_e32 v170, 16, v158
	v_and_b32_e32 v171, 0xffff0000, v158
	v_pk_mul_f32 v[162:163], v[152:153], v[162:163]
	v_lshlrev_b32_e32 v158, 16, v159
	v_and_b32_e32 v159, 0xffff0000, v159
	v_pk_fma_f32 v[158:159], v[148:149], v[158:159], v[162:163]
	v_lshlrev_b32_e32 v162, 16, v155
	v_and_b32_e32 v163, 0xffff0000, v155
	v_pk_fma_f32 v[158:159], v[144:145], v[162:163], v[158:159]
	v_lshlrev_b32_e32 v162, 16, v160
	v_pk_mul_f32 v[158:159], v[204:205], v[158:159]
	v_and_b32_e32 v163, 0xffff0000, v160
	v_cvt_pk_bf16_f32 v155, v158, v159
	v_lshlrev_b32_e32 v158, 16, v164
	v_and_b32_e32 v159, 0xffff0000, v164
	v_pk_mul_f32 v[158:159], v[130:131], v[158:159]
	v_mov_b32_e32 v187, v186
	v_pk_fma_f32 v[158:159], v[134:135], v[162:163], v[158:159]
	v_lshlrev_b32_e32 v162, 16, v156
	v_and_b32_e32 v163, 0xffff0000, v156
	v_pk_mul_f32 v[212:213], v[18:19], v[186:187]
	v_pk_fma_f32 v[158:159], v[138:139], v[162:163], v[158:159]
	v_pk_mul_f32 v[168:169], v[150:151], v[168:169]
	v_pk_mul_f32 v[158:159], v[212:213], v[158:159]
	v_lshlrev_b32_e32 v160, 16, v161
	v_cvt_pk_bf16_f32 v156, v158, v159
	v_lshlrev_b32_e32 v158, 16, v165
	v_and_b32_e32 v159, 0xffff0000, v165
	v_pk_mul_f32 v[158:159], v[132:133], v[158:159]
	v_and_b32_e32 v161, 0xffff0000, v161
	v_pk_fma_f32 v[168:169], v[146:147], v[170:171], v[168:169]
	v_lshlrev_b32_e32 v170, 16, v154
	v_and_b32_e32 v171, 0xffff0000, v154
	v_pk_fma_f32 v[158:159], v[136:137], v[160:161], v[158:159]
	v_lshlrev_b32_e32 v160, 16, v157
	v_and_b32_e32 v161, 0xffff0000, v157
	v_pk_mul_f32 v[208:209], v[26:27], v[186:187]
	v_pk_fma_f32 v[168:169], v[142:143], v[170:171], v[168:169]
	v_pk_fma_f32 v[158:159], v[140:141], v[160:161], v[158:159]
	v_pk_mul_f32 v[168:169], v[208:209], v[168:169]
	v_pk_mul_f32 v[158:159], v[210:211], v[158:159]
	v_cvt_pk_bf16_f32 v154, v168, v169
	v_cvt_pk_bf16_f32 v157, v158, v159
	s_and_saveexec_b64 s[6:7], s[88:89]
	s_xor_b64 s[6:7], exec, s[6:7]
	s_cbranch_execz .LBB0_410
	v_lshl_add_u64 v[158:159], v[206:207], 1, v[228:229]
	v_subrev_u32_e32 v172, s74, v158
	v_bfe_u32 v174, v172, 4, 7
	v_lshrrev_b32_e32 v172, 11, v172
	v_lshlrev_b32_e32 v174, 18, v174
	v_lshl_or_b32 v172, v172, 4, v174
	v_mov_b32_e32 v173, 0
	v_lshl_add_u64 v[172:173], s[74:75], 0, v[172:173]
	global_store_dwordx4 v[172:173], v[154:157], off

; __device__ __forceinline__ unsigned cvt_pk_bf16(float lo, float hi) { f32x2_t v = {lo, hi}; bf16x2_t b = __builtin_convertvector(v, bf16x2_t); return __builtin_bit_cast(unsigned, b); }
;     __device__ __forceinline__ void operator()(const f32x4 (&acc)[2][2][4][2], const Unit& u, int wr, int wc, int fr, int fq) const {
;     ...
;                     for (int m = 0; m < 4; ++m) { const int row = row0 + ai * HALF + m * 16, sq = row & 8191, lr = row & 255; const float r = rr[ai][m];
;                         const bool up_in = lr != 0, dn_in = lr != 255, up_halo = !up_in && sq != 0, dn_halo = !dn_in && sq != 8191;
;                         const bf16_t* up = U + (size_t)row * 1024 + col; const u32x4 z0 = {0u, 0u, 0u, 0u};
;                         const u32x4 uc = *(const u32x4*)up, ul = up_in ? *(const u32x4*)(up - 1024) : z0, ur = dn_in ? *(const u32x4*)(up + 1024) : z0;
;                         const f32x4 b0 = acc[ai][bj][m][0] * r, b1 = acc[ai][bj][m][1] * r;
;                         u32x4 w;
;                         w.x = cvt_pk_bf16(b0[0] * (k0a[0] * bf_lo(ul.x) + k1a[0] * bf_lo(uc.x) + k2a[0] * bf_lo(ur.x)), b0[1] * (k0a[1] * bf_hi(ul.x) + k1a[1] * bf_hi(uc.x) + k2a[1] * bf_hi(ur.x)));
;                         w.y = cvt_pk_bf16(b0[2] * (k0a[2] * bf_lo(ul.y) + k1a[2] * bf_lo(uc.y) + k2a[2] * bf_lo(ur.y)), b0[3] * (k0a[3] * bf_hi(ul.y) + k1a[3] * bf_hi(uc.y) + k2a[3] * bf_hi(ur.y)));
;                         w.z = cvt_pk_bf16(b1[0] * (k0b[0] * bf_lo(ul.z) + k1b[0] * bf_lo(uc.z) + k2b[0] * bf_lo(ur.z)), b1[1] * (k0b[1] * bf_hi(ul.z) + k1b[1] * bf_hi(uc.z) + k2b[1] * bf_hi(ur.z)));
;                         w.w = cvt_pk_bf16(b1[2] * (k0b[2] * bf_lo(ul.w) + k1b[2] * bf_lo(uc.w) + k2b[2] * bf_lo(ur.w)), b1[3] * (k0b[3] * bf_hi(ul.w) + k1b[3] * bf_hi(uc.w) + k2b[3] * bf_hi(ur.w)));
;                         if (up_halo || dn_halo) { const size_t ho = (size_t)(2 * u.pm + (dn_halo ? 1 : 0)) * 1024 + col;
;                             u32x4 bw; bw.x = cvt_pk_bf16(b0[0], b0[1]); bw.y = cvt_pk_bf16(b0[2], b0[3]); bw.z = cvt_pk_bf16(b1[0], b1[1]); bw.w = cvt_pk_bf16(b1[2], b1[3]);
;                             *(u32x4*)(HZ + ho) = w; *(u32x4*)(HBg + ho) = bw; }
;                         else *(u32x4*)(Z + (size_t)row * 1024 + col) = w; }
.LBB0_416:
	s_or_b64 exec, exec, s[6:7]
	v_mov_b32_e32 v168, v184
	v_mov_b32_e32 v169, v184
	v_pk_mul_f32 v[204:205], v[12:13], v[168:169]
	v_pk_mul_f32 v[210:211], v[4:5], v[168:169]
	s_waitcnt lgkmcnt(0)
	v_lshlrev_b32_e32 v168, 16, v162
	v_and_b32_e32 v169, 0xffff0000, v162
	v_pk_mul_f32 v[150:151], v[150:151], v[168:169]
	v_lshlrev_b32_e32 v168, 16, v158
	v_and_b32_e32 v169, 0xffff0000, v158
	v_pk_fma_f32 v[146:147], v[146:147], v[168:169], v[150:151]
	v_lshlrev_b32_e32 v150, 16, v154
	v_and_b32_e32 v151, 0xffff0000, v154
	v_pk_fma_f32 v[142:143], v[142:143], v[150:151], v[146:147]
	v_lshlrev_b32_e32 v146, 16, v163
	v_and_b32_e32 v147, 0xffff0000, v163
	v_pk_mul_f32 v[146:147], v[152:153], v[146:147]
	v_lshlrev_b32_e32 v150, 16, v159
	v_and_b32_e32 v151, 0xffff0000, v159
	v_mov_b32_e32 v185, v184
	v_pk_fma_f32 v[146:147], v[148:149], v[150:151], v[146:147]
	v_lshlrev_b32_e32 v148, 16, v155
	v_and_b32_e32 v149, 0xffff0000, v155
	v_pk_mul_f32 v[208:209], v[10:11], v[184:185]
	v_pk_fma_f32 v[144:145], v[144:145], v[148:149], v[146:147]
	v_pk_mul_f32 v[142:143], v[208:209], v[142:143]
	v_pk_mul_f32 v[144:145], v[204:205], v[144:145]
	v_cvt_pk_bf16_f32 v142, v142, v143
	v_cvt_pk_bf16_f32 v143, v144, v145
	v_lshlrev_b32_e32 v144, 16, v164
	v_and_b32_e32 v145, 0xffff0000, v164
	v_pk_mul_f32 v[130:131], v[130:131], v[144:145]
	v_lshlrev_b32_e32 v144, 16, v160
	v_and_b32_e32 v145, 0xffff0000, v160
	v_pk_fma_f32 v[130:131], v[134:135], v[144:145], v[130:131]
	v_lshlrev_b32_e32 v134, 16, v156
	v_and_b32_e32 v135, 0xffff0000, v156
	v_pk_mul_f32 v[212:213], v[2:3], v[184:185]
	v_pk_fma_f32 v[130:131], v[138:139], v[134:135], v[130:131]
	s_nop 0
	v_pk_mul_f32 v[130:131], v[212:213], v[130:131]
	s_nop 0
	v_cvt_pk_bf16_f32 v144, v130, v131
	v_lshlrev_b32_e32 v130, 16, v165
	v_and_b32_e32 v131, 0xffff0000, v165
	v_pk_mul_f32 v[130:131], v[132:133], v[130:131]
	v_lshlrev_b32_e32 v132, 16, v161
	v_and_b32_e32 v133, 0xffff0000, v161
	v_pk_fma_f32 v[130:131], v[136:137], v[132:133], v[130:131]
	v_lshlrev_b32_e32 v132, 16, v157
	v_and_b32_e32 v133, 0xffff0000, v157
	v_pk_fma_f32 v[130:131], v[140:141], v[132:133], v[130:131]
	s_nop 0
	v_pk_mul_f32 v[130:131], v[210:211], v[130:131]
	s_nop 0
	v_cvt_pk_bf16_f32 v145, v130, v131
	s_and_saveexec_b64 s[6:7], vcc
	s_xor_b64 s[6:7], exec, s[6:7]
	s_cbranch_execz .LBB0_418
	v_lshl_add_u64 v[130:131], v[206:207], 1, v[202:203]
	v_subrev_u32_e32 v172, s74, v130
	v_bfe_u32 v174, v172, 4, 7
	v_lshrrev_b32_e32 v172, 11, v172
	v_lshlrev_b32_e32 v174, 18, v174
	v_lshl_or_b32 v172, v172, 4, v174
	v_mov_b32_e32 v173, 0
	v_lshl_add_u64 v[172:173], s[74:75], 0, v[172:173]
	global_store_dwordx4 v[172:173], v[142:145], off

; __device__ __forceinline__ unsigned cvt_pk_bf16(float lo, float hi) { f32x2_t v = {lo, hi}; bf16x2_t b = __builtin_convertvector(v, bf16x2_t); return __builtin_bit_cast(unsigned, b); }
; #define GAS __attribute__((address_space(1)))
; __device__ __forceinline__ void conv_halo_fix(int pm, const bf16* U, const bf16* HZ, const bf16* HBg, const float* taps, bf16* Z) {
;     int t_l = threadIdx.x; asm volatile("" : "+v"(t_l));
;     const int t = t_l, side = t >> 8, c4 = (t & 255) * 4, row = side ? 256 * pm + 255 : 256 * pm, sq = row & (SEQ - 1);
;     if (side ? (sq != SEQ - 1) : (sq != 0)) {
;         const size_t ho = (size_t)(2 * pm + side) * 1024 + c4; const int nrow = side ? row + 1 : row - 1;
;         const v2u zp = *(const GAS v2u*)(HZ + ho), b = *(const GAS v2u*)(HBg + ho), un = *(const GAS v2u*)(U + (size_t)nrow * 1024 + c4); const f32x4 k = *(const GAS f32x4*)(taps + (side ? 2048 : 0) + c4);
;         v2u o; o.x = pg8::cvt_pk_bf16(bflo(zp.x) + bflo(b.x) * k[0] * bflo(un.x), bfhi(zp.x) + bfhi(b.x) * k[1] * bfhi(un.x));
;         o.y = pg8::cvt_pk_bf16(bflo(zp.y) + bflo(b.y) * k[2] * bflo(un.y), bfhi(zp.y) + bfhi(b.y) * k[3] * bfhi(un.y));
;         *(GAS v2u*)(Z + (size_t)row * 1024 + c4) = o;
;     }
;     asm volatile("s_waitcnt vmcnt(0)" ::: "memory");
;     __syncthreads();
; }
.LBB0_495:
	s_waitcnt lgkmcnt(0)
	v_mov_b32_e32 v3, v0
	s_movk_i32 s0, 0xff
	s_mov_b64 s[12:13], 0
	v_cmp_lt_u32_e32 vcc, s0, v3
	s_lshl_b32 s0, s16, 8
	s_or_b32 s2, s0, 0xff
	v_mov_b32_e32 v4, s0
	s_movk_i32 s0, 0x100
	v_mov_b32_e32 v2, s2
	v_cmp_gt_u32_e64 s[38:39], s0, v3
	s_nop 1
	v_cndmask_b32_e64 v2, v2, v4, s[38:39]
	v_and_b32_e32 v6, 0x1fff, v2
	s_and_saveexec_b64 s[2:3], vcc
	s_xor_b64 s[10:11], exec, s[2:3]
	s_movk_i32 s0, 0x1fff
	v_cmp_ne_u32_e32 vcc, s0, v6
	s_and_b64 s[12:13], vcc, exec
	s_or_saveexec_b64 s[10:11], s[10:11]
	v_mov_b64_e32 v[4:5], 0x800
	v_mov_b32_e32 v5, 1
	s_xor_b64 exec, exec, s[10:11]
	v_cmp_ne_u32_e32 vcc, 0, v6
	v_mov_b64_e32 v[4:5], 0
	s_andn2_b64 s[2:3], s[12:13], exec
	s_and_b64 s[12:13], vcc, exec
	v_mov_b32_e32 v5, -1
	s_or_b64 s[12:13], s[2:3], s[12:13]
	s_or_b64 exec, exec, s[10:11]
	s_and_saveexec_b64 s[10:11], s[12:13]
	s_cbranch_execz .LBB0_486
	v_ashrrev_i32_e32 v6, 8, v3
	v_lshlrev_b32_e32 v3, 2, v3
	v_lshl_add_u32 v6, s16, 1, v6
	v_and_b32_e32 v3, 0x3fc, v3
	v_ashrrev_i32_e32 v7, 31, v6
	v_lshlrev_b64 v[6:7], 11, v[6:7]
	v_lshlrev_b32_e32 v166, 1, v3
	v_readlane_b32 s2, v252, 23
	v_or_b32_e32 v6, v6, v166
	v_readlane_b32 s3, v252, 24
	v_add_u32_e32 v8, v5, v2
	v_ashrrev_i32_e32 v9, 31, v8
	v_lshl_add_u64 v[10:11], s[2:3], 0, v[6:7]
	v_readlane_b32 s2, v253, 39
	v_readlane_b32 s3, v253, 40
	global_load_dwordx2 v[10:11], v[10:11], off
	v_lshlrev_b32_e32 v4, 2, v4
	v_lshl_add_u64 v[6:7], s[2:3], 0, v[6:7]
	v_readlane_b32 s2, v252, 21
	global_load_dwordx2 v[12:13], v[6:7], off
	v_lshlrev_b64 v[6:7], 11, v[8:9]
	v_readlane_b32 s3, v252, 22
	v_mov_b32_e32 v5, v167
	v_lshl_add_u64 v[4:5], s[6:7], 0, v[4:5]
	v_lshl_add_u64 v[6:7], s[2:3], 0, v[6:7]
	v_lshl_add_u64 v[6:7], v[6:7], 0, v[166:167]
	global_load_dwordx2 v[8:9], v[6:7], off
	v_lshlrev_b32_e32 v6, 2, v3
	v_mov_b32_e32 v7, v167
	v_lshl_add_u64 v[4:5], v[4:5], 0, v[6:7]
	global_load_dwordx4 v[4:7], v[4:5], off
	v_ashrrev_i32_e32 v3, 31, v2
	v_lshlrev_b32_e32 v2, 4, v2
	v_lshrrev_b32_e32 v3, 4, v166
	v_lshl_or_b32 v2, v3, 18, v2
	v_and_b32_e32 v3, 15, v166
	v_or_b32_e32 v2, v2, v3
	v_mov_b32_e32 v3, 0
	v_lshl_add_u64 v[2:3], s[74:75], 0, v[2:3]
	s_waitcnt vmcnt(0)
	v_lshlrev_b32_e32 v14, 16, v10
	v_and_b32_e32 v15, 0xffff0000, v10
	v_lshlrev_b32_e32 v10, 16, v11
	v_and_b32_e32 v11, 0xffff0000, v11
	s_waitcnt vmcnt(2)
	v_lshlrev_b32_e32 v16, 16, v12
	v_and_b32_e32 v17, 0xffff0000, v12
	v_lshlrev_b32_e32 v12, 16, v13
	v_and_b32_e32 v13, 0xffff0000, v13
	s_waitcnt vmcnt(0)
	v_pk_mul_f32 v[4:5], v[4:5], v[16:17]
	v_lshlrev_b32_e32 v16, 16, v8
	v_and_b32_e32 v17, 0xffff0000, v8
	v_pk_mul_f32 v[6:7], v[6:7], v[12:13]
	v_lshlrev_b32_e32 v8, 16, v9
	v_and_b32_e32 v9, 0xffff0000, v9
	v_pk_fma_f32 v[4:5], v[4:5], v[16:17], v[14:15]
	v_pk_fma_f32 v[6:7], v[6:7], v[8:9], v[10:11]
	v_cvt_pk_bf16_f32 v4, v4, v5
	v_cvt_pk_bf16_f32 v5, v6, v7
	global_store_dwordx2 v[2:3], v[4:5], off
	s_branch .LBB0_486

;     ...
;     const int tid = tid_l, wid = __builtin_amdgcn_readfirstlane(tid >> 6), lane = tid & 63, wr = wid >> 2, wc = wid & 3, fr = lane & 15, fq = lane >> 4;
;     int K_l = g.K; asm volatile("" : "+s"(K_l));
;     const int K = K_l, nt = K / BK;
;     const bf16_t* gA = g.A; const bf16_t* gB = g.Bt; asm volatile("" : "+s"(gA), "+s"(gB));
;     unsigned voffA[2], voffB[2];
; #pragma unroll
;     for (int i = 0; i < 2; ++i) { int R, C; stage_rc(tid * 16 + i * 8192, R, C); const int Rb = Epi::PERM ? ((R & ~31) + perm32(R & 31)) : R;
;         voffA[i] = (unsigned)(R * (LDA ? LDA : K) + C) * 2u; voffB[i] = (unsigned)(Rb * K + C) * 2u; }
; __global__ void __launch_bounds__(NWAVES * 64, 2) mk_fwd(Args args) {
;     ...
;         if (IN(p + 3)) { const bf16* Wt = (i & 1) ? (const bf16*)(ws + WS_WFO) + (size_t)j * 1024 * 1024 : (const bf16*)(ws + WS_WCO) + (size_t)j * 1024 * 1024;
;             pg8::Gemm g{ZY, Wt, M, D, D}; pg8::StaticOrder S; S.init(M, D, F.G, (int)blockIdx.x);
;             if ((i & 1) == 0) { pg8::Unit uu; for (int k = 0; S.next(k, uu); ++k) conv_halo_fix(uu.pm, UU, HALO, HALO + 128 * 1024, I.conv_k + (size_t)j * 3 * 1024, ZY); }
;             pg8::EpiResid E{HB, ssq};
;             pg8::gemm_phase<pg8::EpiResid, pg8::StaticOrder, true, true>(F.lds + RING_OFF, g, S, E); }
.LBB0_502:
	v_readlane_b32 s2, v254, 53
	v_readlane_b32 s3, v254, 54
	s_and_b64 s[2:3], s[2:3], exec
	v_readlane_b32 s0, v253, 44
	v_readlane_b32 s2, v253, 46
	s_cselect_b32 s0, s2, s0
	v_readlane_b32 s2, v253, 43
	v_readlane_b32 s3, v253, 45
	s_cselect_b32 s2, s3, s2
	s_lshl_b32 s3, s76, 21
	s_add_u32 s44, s2, s3
	v_readlane_b32 s2, v252, 27
	v_mov_b32_e32 v2, v0
	v_readlane_b32 s3, v252, 28
	s_addc_u32 s45, s0, 0
	s_movk_i32 s10, 0x400
	v_readfirstlane_b32 s20, v2
	s_mov_b64 s[58:59], s[74:75]
	s_andn2_b64 vcc, exec, s[2:3]
	v_writelane_b32 v255, s16, 17
	s_cbranch_vccnz .LBB0_543
	s_waitcnt lgkmcnt(0)
	v_lshlrev_b32_e32 v3, 4, v2
	v_add_u32_e32 v4, 0x2000, v3
	v_ashrrev_i32_e32 v5, 31, v4
	v_lshrrev_b32_e32 v5, 22, v5
	v_add_u32_e32 v5, v4, v5
	v_ashrrev_i32_e32 v5, 10, v5
	v_mul_i32_i24_e32 v6, 0x400, v5
	v_sub_u32_e32 v4, v4, v6
	v_lshrrev_b32_e32 v6, 4, v4
	v_bitop3_b32 v6, v6, v4, 32 bitop3:0x6c
	v_ashrrev_i32_e32 v4, 31, v6
	v_lshrrev_b32_e32 v4, 26, v4
	v_add_u32_e32 v7, v6, v4
	v_lshlrev_b32_e32 v8, 3, v5
	v_ashrrev_i32_e32 v4, 6, v7
	v_and_b32_e32 v8, 0x7ffffff0, v8
	v_add_u32_e32 v8, v4, v8
	v_lshlrev_b32_e32 v4, 5, v5
	v_and_b32_e32 v4, 32, v4
	v_mad_u64_u32 v[4:5], s[2:3], v8, s10, v[4:5]
	v_and_b32_e32 v5, 0xc0, v7
	v_sub_u32_e32 v5, v6, v5
	v_ashrrev_i16_sdwa v5, v243, sext(v5) dst_sel:DWORD dst_unused:UNUSED_PAD src0_sel:DWORD src1_sel:BYTE_0
	v_bfe_i32 v5, v5, 0, 16
	v_add_lshl_u32 v130, v4, v5, 1
	v_bfe_i32 v4, v2, 27, 1
	v_lshrrev_b32_e32 v4, 22, v4
	v_add_u32_e32 v4, v3, v4
	v_and_b32_e32 v4, 0xfffffc00, v4
	v_sub_u32_e32 v3, v3, v4
	v_lshrrev_b32_e32 v4, 4, v3
	v_ashrrev_i32_e32 v5, 31, v2
	v_bitop3_b32 v3, v4, v3, 32 bitop3:0x6c
	v_lshrrev_b32_e32 v5, 26, v5
	v_ashrrev_i32_e32 v4, 31, v3
	v_add_u32_e32 v5, v2, v5
	v_lshrrev_b32_e32 v4, 26, v4
	v_ashrrev_i32_e32 v5, 6, v5
	v_add_u32_e32 v6, v3, v4
	v_lshlrev_b32_e32 v7, 3, v5
	v_ashrrev_i32_e32 v4, 6, v6
	v_and_b32_e32 v7, 0x7ffffff0, v7
	v_add_u32_e32 v7, v4, v7
	v_lshlrev_b32_e32 v4, 5, v5
	s_ashr_i32 s11, s10, 31
	v_and_b32_e32 v4, 32, v4
	v_readlane_b32 s8, v254, 25
	s_lshl_b64 s[72:73], s[10:11], 9
	v_mad_u64_u32 v[4:5], s[2:3], v7, s10, v[4:5]
	v_readlane_b32 s9, v254, 26
	s_mul_i32 s2, s72, s9
	s_mul_hi_u32 s3, s72, s8
	s_add_i32 s6, s3, s2
	s_lshr_b64 s[2:3], s[10:11], 23
	v_readlane_b32 s12, v254, 29
	s_mul_i32 s3, s2, s8
	v_readlane_b32 s13, v254, 30
	s_add_i32 s3, s6, s3
	s_mul_i32 s6, s72, s13
	s_mul_hi_u32 s7, s72, s12
	s_ashr_i32 s16, s20, 6
	v_and_b32_e32 v5, 0xc0, v6
	s_add_i32 s6, s7, s6
	s_mul_i32 s2, s2, s12
	s_ashr_i32 s17, s20, 8
	s_lshl_b64 s[60:61], s[10:11], 8
	s_lshl_b32 s0, s16, 10
	v_sub_u32_e32 v3, v3, v5
	s_add_i32 s2, s6, s2
	s_mul_i32 s6, s72, s12
	v_ashrrev_i16_sdwa v3, v243, sext(v3) dst_sel:DWORD dst_unused:UNUSED_PAD src0_sel:DWORD src1_sel:BYTE_0
	s_add_u32 s6, s44, s6
	v_bfe_i32 v3, v3, 0, 16
	s_addc_u32 s7, s45, s2
	s_add_i32 s2, s0, 0
	v_add_lshl_u32 v166, v4, v3, 1
	v_readlane_b32 s101, v254, 52
	s_branch .Lop_fourier
	v_mov_b32_e32 v246, v166
	v_mov_b32_e32 v248, v130
	v_mov_b32_e32 v244, 0x80
	s_movk_i32 s101, 0x80
	v_writelane_b32 v255, s101, 40
	s_movk_i32 s101, 0x100
	v_writelane_b32 v255, s101, 41
	s_mov_b32 s101, 0x40000
	s_branch .Lop_setdone
